# v043 plus hand-written sample-attention item (21-deep rolling K/V load pipeline, DPP row reductions)
# speedup vs baseline: 1.0083x; 1.0083x over previous
.LBB0_647:
	s_sub_u32 s0, s89, 0x80
	s_mul_i32 s1, s0, 0xaaab
	s_lshr_b32 s17, s1, 17
	s_mul_i32 s2, s17, 3
	s_sub_i32 s16, s0, s2
	s_lshl_b32 s18, s16, 1
	s_lshl_b32 s15, 0x80, s18
	s_lshl_b32 s14, 0x2000, s18
	v_readlane_b32 s2, v254, 3
	v_readlane_b32 s3, v254, 4
	s_lshl_b32 s0, s16, 3
	s_add_u32 s2, s2, s0
	s_addc_u32 s3, s3, 0
	s_load_dwordx2 s[28:29], s[2:3], 0x10
	s_mov_b32 s0, 0x7895000
	s_cmp_eq_u32 s16, 0
	s_cselect_b32 s0, 0x5895000, s0
	s_cmp_eq_u32 s16, 2
	s_cselect_b32 s0, 0xf895000, s0
	s_mul_i32 s1, s17, s15
	s_lshl_b32 s1, s1, 11
	s_add_u32 s10, s56, s0
	s_addc_u32 s11, s57, 0
	s_add_u32 s10, s10, s1
	s_addc_u32 s11, s11, 0
	s_sub_u32 s10, s10, 0x2000
	s_subb_u32 s11, s11, 0
	v_lshrrev_b32_e32 v241, 4, v166
	v_and_b32_e32 v242, 15, v166
	v_lshlrev_b32_e32 v242, 4, v242
	v_xor_b32_e32 v243, 16, v166
	v_lshlrev_b32_e32 v243, 2, v243
	v_xor_b32_e32 v244, 32, v166
	v_lshlrev_b32_e32 v244, 2, v244
	s_mul_i32 s0, s86, 0x210
	v_lshl_add_u32 v240, v241, 2, s0
	v_lshl_add_u32 v72, v166, 2, s0
	s_mov_b64 s[26:27], exec
	s_mov_b64 s[24:25], 0xffff
	s_lshr_b32 s34, s86, 1
	s_lshl_b32 s35, s34, 8
	s_waitcnt lgkmcnt(0)
	s_add_u32 s28, s28, s1
	s_addc_u32 s29, s29, 0
	s_add_u32 s6, s28, s35
	s_addc_u32 s7, s29, 0
	s_add_u32 s8, s6, 0x400
	s_addc_u32 s9, s7, 0
	s_add_u32 s10, s10, s35
	s_addc_u32 s11, s11, 0
	s_barrier
.Las_A:
	s_and_b32 s19, s86, 1
	s_lshl_b32 s19, s19, 1
	s_lshl_b32 s0, s17, 2
	s_add_u32 s0, s0, s19
	s_mul_i32 s0, s0, 0xc00
	s_lshl_b32 s1, s16, 10
	s_add_u32 s0, s0, s1
	s_add_u32 s0, s0, s35
	s_add_u32 s12, s58, 0x86d6000
	s_addc_u32 s13, s59, 0
	s_add_u32 s12, s12, s0
	s_addc_u32 s13, s13, 0
	global_load_dwordx4 v[220:223], v242, s[12:13]
	s_and_b32 s19, s86, 1
	s_lshl_b32 s19, s19, 1
	v_lshlrev_b32_e32 v210, s18, v241
	s_add_u32 s0, s15, s19
	v_sub_u32_e32 v210, s0, v210
	v_cmp_le_u32_e32 vcc, s15, v210
	v_lshlrev_b32_e32 v210, 11, v210
	v_add_u32_e32 v210, v210, v242
	v_mov_b32_e32 v212, s6
	v_mov_b32_e32 v213, s7
	v_mov_b32_e32 v214, s10
	v_mov_b32_e32 v215, s11
	v_cndmask_b32_e32 v212, v212, v214, vcc
	v_cndmask_b32_e32 v213, v213, v215, vcc
	v_mov_b32_e32 v211, 0
	v_lshl_add_u64 v[212:213], v[212:213], 0, v[210:211]
	global_load_dwordx4 v[0:3], v[212:213], off
	v_add_u32_e32 v238, 4, v241
	v_lshlrev_b32_e32 v238, s18, v238
	s_add_u32 s0, s15, s19
	v_sub_u32_e32 v238, s0, v238
	v_lshl_add_u32 v238, v238, 11, v242
	global_load_dwordx4 v[4:7], v238, s[6:7]
	v_subrev_u32_e32 v238, s14, v238
	global_load_dwordx4 v[8:11], v238, s[6:7]
	v_subrev_u32_e32 v238, s14, v238
	global_load_dwordx4 v[12:15], v238, s[6:7]
	v_subrev_u32_e32 v238, s14, v238
	global_load_dwordx4 v[16:19], v238, s[6:7]
	v_subrev_u32_e32 v238, s14, v238
	global_load_dwordx4 v[20:23], v238, s[6:7]
	v_subrev_u32_e32 v238, s14, v238
	global_load_dwordx4 v[24:27], v238, s[6:7]
	v_subrev_u32_e32 v238, s14, v238
	global_load_dwordx4 v[28:31], v238, s[6:7]
	v_subrev_u32_e32 v238, s14, v238
	global_load_dwordx4 v[32:35], v238, s[6:7]
	v_subrev_u32_e32 v238, s14, v238
	global_load_dwordx4 v[36:39], v238, s[6:7]
	v_subrev_u32_e32 v238, s14, v238
	global_load_dwordx4 v[40:43], v238, s[6:7]
	v_subrev_u32_e32 v238, s14, v238
	global_load_dwordx4 v[44:47], v238, s[6:7]
	v_subrev_u32_e32 v238, s14, v238
	global_load_dwordx4 v[48:51], v238, s[6:7]
	v_subrev_u32_e32 v238, s14, v238
	global_load_dwordx4 v[52:55], v238, s[6:7]
	v_subrev_u32_e32 v238, s14, v238
	global_load_dwordx4 v[56:59], v238, s[6:7]
	v_subrev_u32_e32 v238, s14, v238
	global_load_dwordx4 v[60:63], v238, s[6:7]
	v_subrev_u32_e32 v238, s14, v238
	global_load_dwordx4 v[64:67], v238, s[6:7]
	v_subrev_u32_e32 v238, s14, v238
	global_load_dwordx4 v[68:71], v238, s[6:7]
	v_subrev_u32_e32 v238, s14, v238
	global_load_dwordx4 v[196:199], v238, s[6:7]
	v_subrev_u32_e32 v238, s14, v238
	global_load_dwordx4 v[200:203], v238, s[6:7]
	v_subrev_u32_e32 v238, s14, v238
	global_load_dwordx4 v[204:207], v238, s[6:7]
	v_subrev_u32_e32 v238, s14, v238
	s_waitcnt vmcnt(18)
	s_waitcnt vmcnt(21)
	v_mul_f32_e32 v220, 0x3e000000, v220
	v_mul_f32_e32 v221, 0x3e000000, v221
	v_mul_f32_e32 v222, 0x3e000000, v222
	v_mul_f32_e32 v223, 0x3e000000, v223
	v_mul_f32_e32 v232, v0, v220
	v_mul_f32_e32 v233, v4, v220
	v_mul_f32_e32 v234, v8, v220
	v_fmac_f32_e32 v232, v1, v221
	v_fmac_f32_e32 v233, v5, v221
	v_fmac_f32_e32 v234, v9, v221
	v_fmac_f32_e32 v232, v2, v222
	v_fmac_f32_e32 v233, v6, v222
	v_fmac_f32_e32 v234, v10, v222
	v_fmac_f32_e32 v232, v3, v223
	v_fmac_f32_e32 v233, v7, v223
	v_fmac_f32_e32 v234, v11, v223
	global_load_dwordx4 v[0:3], v238, s[6:7]
	v_subrev_u32_e32 v238, s14, v238
	global_load_dwordx4 v[4:7], v238, s[6:7]
	v_subrev_u32_e32 v238, s14, v238
	global_load_dwordx4 v[8:11], v238, s[6:7]
	v_subrev_u32_e32 v238, s14, v238
	v_add_f32_dpp v232, v232, v232 quad_perm:[1,0,3,2] row_mask:0xf bank_mask:0xf
	v_add_f32_dpp v233, v233, v233 quad_perm:[1,0,3,2] row_mask:0xf bank_mask:0xf
	v_add_f32_dpp v234, v234, v234 quad_perm:[1,0,3,2] row_mask:0xf bank_mask:0xf
	v_add_f32_dpp v232, v232, v232 quad_perm:[2,3,0,1] row_mask:0xf bank_mask:0xf
	v_add_f32_dpp v233, v233, v233 quad_perm:[2,3,0,1] row_mask:0xf bank_mask:0xf
	v_add_f32_dpp v234, v234, v234 quad_perm:[2,3,0,1] row_mask:0xf bank_mask:0xf
	v_add_f32_dpp v232, v232, v232 row_half_mirror row_mask:0xf bank_mask:0xf
	v_add_f32_dpp v233, v233, v233 row_half_mirror row_mask:0xf bank_mask:0xf
	v_add_f32_dpp v234, v234, v234 row_half_mirror row_mask:0xf bank_mask:0xf
	v_add_f32_dpp v232, v232, v232 row_mirror row_mask:0xf bank_mask:0xf
	v_add_f32_dpp v233, v233, v233 row_mirror row_mask:0xf bank_mask:0xf
	v_add_f32_dpp v234, v234, v234 row_mirror row_mask:0xf bank_mask:0xf
	s_nop 0
	ds_write_b32 v240, v232
	ds_write_b32 v240, v233 offset:16
	ds_write_b32 v240, v234 offset:32
	s_waitcnt vmcnt(18)
	v_mul_f32_e32 v232, v12, v220
	v_mul_f32_e32 v233, v16, v220
	v_mul_f32_e32 v234, v20, v220
	v_fmac_f32_e32 v232, v13, v221
	v_fmac_f32_e32 v233, v17, v221
	v_fmac_f32_e32 v234, v21, v221
	v_fmac_f32_e32 v232, v14, v222
	v_fmac_f32_e32 v233, v18, v222
	v_fmac_f32_e32 v234, v22, v222
	v_fmac_f32_e32 v232, v15, v223
	v_fmac_f32_e32 v233, v19, v223
	v_fmac_f32_e32 v234, v23, v223
	global_load_dwordx4 v[12:15], v238, s[6:7]
	v_subrev_u32_e32 v238, s14, v238
	global_load_dwordx4 v[16:19], v238, s[6:7]
	v_subrev_u32_e32 v238, s14, v238
	global_load_dwordx4 v[20:23], v238, s[6:7]
	v_subrev_u32_e32 v238, s14, v238
	v_add_f32_dpp v232, v232, v232 quad_perm:[1,0,3,2] row_mask:0xf bank_mask:0xf
	v_add_f32_dpp v233, v233, v233 quad_perm:[1,0,3,2] row_mask:0xf bank_mask:0xf
	v_add_f32_dpp v234, v234, v234 quad_perm:[1,0,3,2] row_mask:0xf bank_mask:0xf
	v_add_f32_dpp v232, v232, v232 quad_perm:[2,3,0,1] row_mask:0xf bank_mask:0xf
	v_add_f32_dpp v233, v233, v233 quad_perm:[2,3,0,1] row_mask:0xf bank_mask:0xf
	v_add_f32_dpp v234, v234, v234 quad_perm:[2,3,0,1] row_mask:0xf bank_mask:0xf
	v_add_f32_dpp v232, v232, v232 row_half_mirror row_mask:0xf bank_mask:0xf
	v_add_f32_dpp v233, v233, v233 row_half_mirror row_mask:0xf bank_mask:0xf
	v_add_f32_dpp v234, v234, v234 row_half_mirror row_mask:0xf bank_mask:0xf
	v_add_f32_dpp v232, v232, v232 row_mirror row_mask:0xf bank_mask:0xf
	v_add_f32_dpp v233, v233, v233 row_mirror row_mask:0xf bank_mask:0xf
	v_add_f32_dpp v234, v234, v234 row_mirror row_mask:0xf bank_mask:0xf
	s_nop 0
	ds_write_b32 v240, v232 offset:48
	ds_write_b32 v240, v233 offset:64
	ds_write_b32 v240, v234 offset:80
	s_waitcnt vmcnt(18)
	v_mul_f32_e32 v232, v24, v220
	v_mul_f32_e32 v233, v28, v220
	v_mul_f32_e32 v234, v32, v220
	v_fmac_f32_e32 v232, v25, v221
	v_fmac_f32_e32 v233, v29, v221
	v_fmac_f32_e32 v234, v33, v221
	v_fmac_f32_e32 v232, v26, v222
	v_fmac_f32_e32 v233, v30, v222
	v_fmac_f32_e32 v234, v34, v222
	v_fmac_f32_e32 v232, v27, v223
	v_fmac_f32_e32 v233, v31, v223
	v_fmac_f32_e32 v234, v35, v223
	global_load_dwordx4 v[24:27], v238, s[6:7]
	v_subrev_u32_e32 v238, s14, v238
	global_load_dwordx4 v[28:31], v238, s[6:7]
	v_subrev_u32_e32 v238, s14, v238
	global_load_dwordx4 v[32:35], v238, s[6:7]
	v_subrev_u32_e32 v238, s14, v238
	v_add_f32_dpp v232, v232, v232 quad_perm:[1,0,3,2] row_mask:0xf bank_mask:0xf
	v_add_f32_dpp v233, v233, v233 quad_perm:[1,0,3,2] row_mask:0xf bank_mask:0xf
	v_add_f32_dpp v234, v234, v234 quad_perm:[1,0,3,2] row_mask:0xf bank_mask:0xf
	v_add_f32_dpp v232, v232, v232 quad_perm:[2,3,0,1] row_mask:0xf bank_mask:0xf
	v_add_f32_dpp v233, v233, v233 quad_perm:[2,3,0,1] row_mask:0xf bank_mask:0xf
	v_add_f32_dpp v234, v234, v234 quad_perm:[2,3,0,1] row_mask:0xf bank_mask:0xf
	v_add_f32_dpp v232, v232, v232 row_half_mirror row_mask:0xf bank_mask:0xf
	v_add_f32_dpp v233, v233, v233 row_half_mirror row_mask:0xf bank_mask:0xf
	v_add_f32_dpp v234, v234, v234 row_half_mirror row_mask:0xf bank_mask:0xf
	v_add_f32_dpp v232, v232, v232 row_mirror row_mask:0xf bank_mask:0xf
	v_add_f32_dpp v233, v233, v233 row_mirror row_mask:0xf bank_mask:0xf
	v_add_f32_dpp v234, v234, v234 row_mirror row_mask:0xf bank_mask:0xf
	s_nop 0
	ds_write_b32 v240, v232 offset:96
	ds_write_b32 v240, v233 offset:112
	ds_write_b32 v240, v234 offset:128
	s_waitcnt vmcnt(18)
	v_mul_f32_e32 v232, v36, v220
	v_mul_f32_e32 v233, v40, v220
	v_mul_f32_e32 v234, v44, v220
	v_fmac_f32_e32 v232, v37, v221
	v_fmac_f32_e32 v233, v41, v221
	v_fmac_f32_e32 v234, v45, v221
	v_fmac_f32_e32 v232, v38, v222
	v_fmac_f32_e32 v233, v42, v222
	v_fmac_f32_e32 v234, v46, v222
	v_fmac_f32_e32 v232, v39, v223
	v_fmac_f32_e32 v233, v43, v223
	v_fmac_f32_e32 v234, v47, v223
	global_load_dwordx4 v[36:39], v238, s[6:7]
	v_subrev_u32_e32 v238, s14, v238
	global_load_dwordx4 v[40:43], v238, s[6:7]
	s_and_b32 s19, s86, 1
	s_lshl_b32 s19, s19, 1
	s_lshl_b32 s0, s19, 11
	v_mov_b32_e32 v210, s0
	v_cmp_eq_u32_e32 vcc, 0, v241
	v_cndmask_b32_e32 v238, 0, v210, vcc
	v_add_u32_e32 v238, v238, v242
	global_load_dwordx4 v[44:47], v238, s[6:7]
	v_add_f32_dpp v232, v232, v232 quad_perm:[1,0,3,2] row_mask:0xf bank_mask:0xf
	v_add_f32_dpp v233, v233, v233 quad_perm:[1,0,3,2] row_mask:0xf bank_mask:0xf
	v_add_f32_dpp v234, v234, v234 quad_perm:[1,0,3,2] row_mask:0xf bank_mask:0xf
	v_add_f32_dpp v232, v232, v232 quad_perm:[2,3,0,1] row_mask:0xf bank_mask:0xf
	v_add_f32_dpp v233, v233, v233 quad_perm:[2,3,0,1] row_mask:0xf bank_mask:0xf
	v_add_f32_dpp v234, v234, v234 quad_perm:[2,3,0,1] row_mask:0xf bank_mask:0xf
	v_add_f32_dpp v232, v232, v232 row_half_mirror row_mask:0xf bank_mask:0xf
	v_add_f32_dpp v233, v233, v233 row_half_mirror row_mask:0xf bank_mask:0xf
	v_add_f32_dpp v234, v234, v234 row_half_mirror row_mask:0xf bank_mask:0xf
	v_add_f32_dpp v232, v232, v232 row_mirror row_mask:0xf bank_mask:0xf
	v_add_f32_dpp v233, v233, v233 row_mirror row_mask:0xf bank_mask:0xf
	v_add_f32_dpp v234, v234, v234 row_mirror row_mask:0xf bank_mask:0xf
	s_nop 0
	ds_write_b32 v240, v232 offset:144
	ds_write_b32 v240, v233 offset:160
	ds_write_b32 v240, v234 offset:176
	s_waitcnt vmcnt(18)
	v_mul_f32_e32 v232, v48, v220
	v_mul_f32_e32 v233, v52, v220
	v_mul_f32_e32 v234, v56, v220
	v_fmac_f32_e32 v232, v49, v221
	v_fmac_f32_e32 v233, v53, v221
	v_fmac_f32_e32 v234, v57, v221
	v_fmac_f32_e32 v232, v50, v222
	v_fmac_f32_e32 v233, v54, v222
	v_fmac_f32_e32 v234, v58, v222
	v_fmac_f32_e32 v232, v51, v223
	v_fmac_f32_e32 v233, v55, v223
	v_fmac_f32_e32 v234, v59, v223
	s_and_b32 s19, s86, 1
	s_lshl_b32 s19, s19, 1
	v_lshlrev_b32_e32 v210, s18, v241
	s_add_u32 s0, s15, s19
	v_sub_u32_e32 v210, s0, v210
	v_cmp_le_u32_e32 vcc, s15, v210
	v_lshlrev_b32_e32 v210, 11, v210
	v_add_u32_e32 v210, v210, v242
	v_add_u32_e32 v210, 0x400, v210
	v_mov_b32_e32 v212, s6
	v_mov_b32_e32 v213, s7
	v_mov_b32_e32 v214, s10
	v_mov_b32_e32 v215, s11
	v_cndmask_b32_e32 v212, v212, v214, vcc
	v_cndmask_b32_e32 v213, v213, v215, vcc
	v_mov_b32_e32 v211, 0
	v_lshl_add_u64 v[212:213], v[212:213], 0, v[210:211]
	global_load_dwordx4 v[48:51], v[212:213], off
	v_add_u32_e32 v239, 4, v241
	v_lshlrev_b32_e32 v239, s18, v239
	s_add_u32 s0, s15, s19
	v_sub_u32_e32 v239, s0, v239
	v_lshl_add_u32 v239, v239, 11, v242
	global_load_dwordx4 v[52:55], v239, s[8:9]
	v_subrev_u32_e32 v239, s14, v239
	global_load_dwordx4 v[56:59], v239, s[8:9]
	v_subrev_u32_e32 v239, s14, v239
	v_add_f32_dpp v232, v232, v232 quad_perm:[1,0,3,2] row_mask:0xf bank_mask:0xf
	v_add_f32_dpp v233, v233, v233 quad_perm:[1,0,3,2] row_mask:0xf bank_mask:0xf
	v_add_f32_dpp v234, v234, v234 quad_perm:[1,0,3,2] row_mask:0xf bank_mask:0xf
	v_add_f32_dpp v232, v232, v232 quad_perm:[2,3,0,1] row_mask:0xf bank_mask:0xf
	v_add_f32_dpp v233, v233, v233 quad_perm:[2,3,0,1] row_mask:0xf bank_mask:0xf
	v_add_f32_dpp v234, v234, v234 quad_perm:[2,3,0,1] row_mask:0xf bank_mask:0xf
	v_add_f32_dpp v232, v232, v232 row_half_mirror row_mask:0xf bank_mask:0xf
	v_add_f32_dpp v233, v233, v233 row_half_mirror row_mask:0xf bank_mask:0xf
	v_add_f32_dpp v234, v234, v234 row_half_mirror row_mask:0xf bank_mask:0xf
	v_add_f32_dpp v232, v232, v232 row_mirror row_mask:0xf bank_mask:0xf
	v_add_f32_dpp v233, v233, v233 row_mirror row_mask:0xf bank_mask:0xf
	v_add_f32_dpp v234, v234, v234 row_mirror row_mask:0xf bank_mask:0xf
	s_nop 0
	ds_write_b32 v240, v232 offset:192
	ds_write_b32 v240, v233 offset:208
	ds_write_b32 v240, v234 offset:224
	s_waitcnt vmcnt(18)
	v_mul_f32_e32 v232, v60, v220
	v_mul_f32_e32 v233, v64, v220
	v_mul_f32_e32 v234, v68, v220
	v_fmac_f32_e32 v232, v61, v221
	v_fmac_f32_e32 v233, v65, v221
	v_fmac_f32_e32 v234, v69, v221
	v_fmac_f32_e32 v232, v62, v222
	v_fmac_f32_e32 v233, v66, v222
	v_fmac_f32_e32 v234, v70, v222
	v_fmac_f32_e32 v232, v63, v223
	v_fmac_f32_e32 v233, v67, v223
	v_fmac_f32_e32 v234, v71, v223
	global_load_dwordx4 v[60:63], v239, s[8:9]
	v_subrev_u32_e32 v239, s14, v239
	global_load_dwordx4 v[64:67], v239, s[8:9]
	v_subrev_u32_e32 v239, s14, v239
	global_load_dwordx4 v[68:71], v239, s[8:9]
	v_subrev_u32_e32 v239, s14, v239
	v_add_f32_dpp v232, v232, v232 quad_perm:[1,0,3,2] row_mask:0xf bank_mask:0xf
	v_add_f32_dpp v233, v233, v233 quad_perm:[1,0,3,2] row_mask:0xf bank_mask:0xf
	v_add_f32_dpp v234, v234, v234 quad_perm:[1,0,3,2] row_mask:0xf bank_mask:0xf
	v_add_f32_dpp v232, v232, v232 quad_perm:[2,3,0,1] row_mask:0xf bank_mask:0xf
	v_add_f32_dpp v233, v233, v233 quad_perm:[2,3,0,1] row_mask:0xf bank_mask:0xf
	v_add_f32_dpp v234, v234, v234 quad_perm:[2,3,0,1] row_mask:0xf bank_mask:0xf
	v_add_f32_dpp v232, v232, v232 row_half_mirror row_mask:0xf bank_mask:0xf
	v_add_f32_dpp v233, v233, v233 row_half_mirror row_mask:0xf bank_mask:0xf
	v_add_f32_dpp v234, v234, v234 row_half_mirror row_mask:0xf bank_mask:0xf
	v_add_f32_dpp v232, v232, v232 row_mirror row_mask:0xf bank_mask:0xf
	v_add_f32_dpp v233, v233, v233 row_mirror row_mask:0xf bank_mask:0xf
	v_add_f32_dpp v234, v234, v234 row_mirror row_mask:0xf bank_mask:0xf
	s_nop 0
	ds_write_b32 v240, v232 offset:240
	ds_write_b32 v240, v233 offset:256
	ds_write_b32 v240, v234 offset:272
	s_waitcnt vmcnt(18)
	v_mul_f32_e32 v232, v196, v220
	v_mul_f32_e32 v233, v200, v220
	v_mul_f32_e32 v234, v204, v220
	v_fmac_f32_e32 v232, v197, v221
	v_fmac_f32_e32 v233, v201, v221
	v_fmac_f32_e32 v234, v205, v221
	v_fmac_f32_e32 v232, v198, v222
	v_fmac_f32_e32 v233, v202, v222
	v_fmac_f32_e32 v234, v206, v222
	v_fmac_f32_e32 v232, v199, v223
	v_fmac_f32_e32 v233, v203, v223
	v_fmac_f32_e32 v234, v207, v223
	global_load_dwordx4 v[196:199], v239, s[8:9]
	v_subrev_u32_e32 v239, s14, v239
	global_load_dwordx4 v[200:203], v239, s[8:9]
	v_subrev_u32_e32 v239, s14, v239
	global_load_dwordx4 v[204:207], v239, s[8:9]
	v_subrev_u32_e32 v239, s14, v239
	v_add_f32_dpp v232, v232, v232 quad_perm:[1,0,3,2] row_mask:0xf bank_mask:0xf
	v_add_f32_dpp v233, v233, v233 quad_perm:[1,0,3,2] row_mask:0xf bank_mask:0xf
	v_add_f32_dpp v234, v234, v234 quad_perm:[1,0,3,2] row_mask:0xf bank_mask:0xf
	v_add_f32_dpp v232, v232, v232 quad_perm:[2,3,0,1] row_mask:0xf bank_mask:0xf
	v_add_f32_dpp v233, v233, v233 quad_perm:[2,3,0,1] row_mask:0xf bank_mask:0xf
	v_add_f32_dpp v234, v234, v234 quad_perm:[2,3,0,1] row_mask:0xf bank_mask:0xf
	v_add_f32_dpp v232, v232, v232 row_half_mirror row_mask:0xf bank_mask:0xf
	v_add_f32_dpp v233, v233, v233 row_half_mirror row_mask:0xf bank_mask:0xf
	v_add_f32_dpp v234, v234, v234 row_half_mirror row_mask:0xf bank_mask:0xf
	v_add_f32_dpp v232, v232, v232 row_mirror row_mask:0xf bank_mask:0xf
	v_add_f32_dpp v233, v233, v233 row_mirror row_mask:0xf bank_mask:0xf
	v_add_f32_dpp v234, v234, v234 row_mirror row_mask:0xf bank_mask:0xf
	s_nop 0
	ds_write_b32 v240, v232 offset:288
	ds_write_b32 v240, v233 offset:304
	ds_write_b32 v240, v234 offset:320
	s_waitcnt vmcnt(18)
	v_mul_f32_e32 v232, v0, v220
	v_mul_f32_e32 v233, v4, v220
	v_mul_f32_e32 v234, v8, v220
	v_fmac_f32_e32 v232, v1, v221
	v_fmac_f32_e32 v233, v5, v221
	v_fmac_f32_e32 v234, v9, v221
	v_fmac_f32_e32 v232, v2, v222
	v_fmac_f32_e32 v233, v6, v222
	v_fmac_f32_e32 v234, v10, v222
	v_fmac_f32_e32 v232, v3, v223
	v_fmac_f32_e32 v233, v7, v223
	v_fmac_f32_e32 v234, v11, v223
	global_load_dwordx4 v[0:3], v239, s[8:9]
	v_subrev_u32_e32 v239, s14, v239
	global_load_dwordx4 v[4:7], v239, s[8:9]
	v_subrev_u32_e32 v239, s14, v239
	global_load_dwordx4 v[8:11], v239, s[8:9]
	v_subrev_u32_e32 v239, s14, v239
	v_add_f32_dpp v232, v232, v232 quad_perm:[1,0,3,2] row_mask:0xf bank_mask:0xf
	v_add_f32_dpp v233, v233, v233 quad_perm:[1,0,3,2] row_mask:0xf bank_mask:0xf
	v_add_f32_dpp v234, v234, v234 quad_perm:[1,0,3,2] row_mask:0xf bank_mask:0xf
	v_add_f32_dpp v232, v232, v232 quad_perm:[2,3,0,1] row_mask:0xf bank_mask:0xf
	v_add_f32_dpp v233, v233, v233 quad_perm:[2,3,0,1] row_mask:0xf bank_mask:0xf
	v_add_f32_dpp v234, v234, v234 quad_perm:[2,3,0,1] row_mask:0xf bank_mask:0xf
	v_add_f32_dpp v232, v232, v232 row_half_mirror row_mask:0xf bank_mask:0xf
	v_add_f32_dpp v233, v233, v233 row_half_mirror row_mask:0xf bank_mask:0xf
	v_add_f32_dpp v234, v234, v234 row_half_mirror row_mask:0xf bank_mask:0xf
	v_add_f32_dpp v232, v232, v232 row_mirror row_mask:0xf bank_mask:0xf
	v_add_f32_dpp v233, v233, v233 row_mirror row_mask:0xf bank_mask:0xf
	v_add_f32_dpp v234, v234, v234 row_mirror row_mask:0xf bank_mask:0xf
	s_nop 0
	ds_write_b32 v240, v232 offset:336
	ds_write_b32 v240, v233 offset:352
	ds_write_b32 v240, v234 offset:368
	s_waitcnt vmcnt(18)
	v_mul_f32_e32 v232, v12, v220
	v_mul_f32_e32 v233, v16, v220
	v_mul_f32_e32 v234, v20, v220
	v_fmac_f32_e32 v232, v13, v221
	v_fmac_f32_e32 v233, v17, v221
	v_fmac_f32_e32 v234, v21, v221
	v_fmac_f32_e32 v232, v14, v222
	v_fmac_f32_e32 v233, v18, v222
	v_fmac_f32_e32 v234, v22, v222
	v_fmac_f32_e32 v232, v15, v223
	v_fmac_f32_e32 v233, v19, v223
	v_fmac_f32_e32 v234, v23, v223
	global_load_dwordx4 v[12:15], v239, s[8:9]
	v_subrev_u32_e32 v239, s14, v239
	global_load_dwordx4 v[16:19], v239, s[8:9]
	v_subrev_u32_e32 v239, s14, v239
	global_load_dwordx4 v[20:23], v239, s[8:9]
	v_subrev_u32_e32 v239, s14, v239
	v_add_f32_dpp v232, v232, v232 quad_perm:[1,0,3,2] row_mask:0xf bank_mask:0xf
	v_add_f32_dpp v233, v233, v233 quad_perm:[1,0,3,2] row_mask:0xf bank_mask:0xf
	v_add_f32_dpp v234, v234, v234 quad_perm:[1,0,3,2] row_mask:0xf bank_mask:0xf
	v_add_f32_dpp v232, v232, v232 quad_perm:[2,3,0,1] row_mask:0xf bank_mask:0xf
	v_add_f32_dpp v233, v233, v233 quad_perm:[2,3,0,1] row_mask:0xf bank_mask:0xf
	v_add_f32_dpp v234, v234, v234 quad_perm:[2,3,0,1] row_mask:0xf bank_mask:0xf
	v_add_f32_dpp v232, v232, v232 row_half_mirror row_mask:0xf bank_mask:0xf
	v_add_f32_dpp v233, v233, v233 row_half_mirror row_mask:0xf bank_mask:0xf
	v_add_f32_dpp v234, v234, v234 row_half_mirror row_mask:0xf bank_mask:0xf
	v_add_f32_dpp v232, v232, v232 row_mirror row_mask:0xf bank_mask:0xf
	v_add_f32_dpp v233, v233, v233 row_mirror row_mask:0xf bank_mask:0xf
	v_add_f32_dpp v234, v234, v234 row_mirror row_mask:0xf bank_mask:0xf
	s_nop 0
	ds_write_b32 v240, v232 offset:384
	ds_write_b32 v240, v233 offset:400
	ds_write_b32 v240, v234 offset:416
	s_waitcnt vmcnt(18)
	v_mul_f32_e32 v232, v24, v220
	v_mul_f32_e32 v233, v28, v220
	v_mul_f32_e32 v234, v32, v220
	v_fmac_f32_e32 v232, v25, v221
	v_fmac_f32_e32 v233, v29, v221
	v_fmac_f32_e32 v234, v33, v221
	v_fmac_f32_e32 v232, v26, v222
	v_fmac_f32_e32 v233, v30, v222
	v_fmac_f32_e32 v234, v34, v222
	v_fmac_f32_e32 v232, v27, v223
	v_fmac_f32_e32 v233, v31, v223
	v_fmac_f32_e32 v234, v35, v223
	global_load_dwordx4 v[24:27], v239, s[8:9]
	v_subrev_u32_e32 v239, s14, v239
	global_load_dwordx4 v[28:31], v239, s[8:9]
	v_subrev_u32_e32 v239, s14, v239
	global_load_dwordx4 v[32:35], v239, s[8:9]
	v_subrev_u32_e32 v239, s14, v239
	v_add_f32_dpp v232, v232, v232 quad_perm:[1,0,3,2] row_mask:0xf bank_mask:0xf
	v_add_f32_dpp v233, v233, v233 quad_perm:[1,0,3,2] row_mask:0xf bank_mask:0xf
	v_add_f32_dpp v234, v234, v234 quad_perm:[1,0,3,2] row_mask:0xf bank_mask:0xf
	v_add_f32_dpp v232, v232, v232 quad_perm:[2,3,0,1] row_mask:0xf bank_mask:0xf
	v_add_f32_dpp v233, v233, v233 quad_perm:[2,3,0,1] row_mask:0xf bank_mask:0xf
	v_add_f32_dpp v234, v234, v234 quad_perm:[2,3,0,1] row_mask:0xf bank_mask:0xf
	v_add_f32_dpp v232, v232, v232 row_half_mirror row_mask:0xf bank_mask:0xf
	v_add_f32_dpp v233, v233, v233 row_half_mirror row_mask:0xf bank_mask:0xf
	v_add_f32_dpp v234, v234, v234 row_half_mirror row_mask:0xf bank_mask:0xf
	v_add_f32_dpp v232, v232, v232 row_mirror row_mask:0xf bank_mask:0xf
	v_add_f32_dpp v233, v233, v233 row_mirror row_mask:0xf bank_mask:0xf
	v_add_f32_dpp v234, v234, v234 row_mirror row_mask:0xf bank_mask:0xf
	s_nop 0
	ds_write_b32 v240, v232 offset:432
	ds_write_b32 v240, v233 offset:448
	ds_write_b32 v240, v234 offset:464
	s_waitcnt vmcnt(18)
	v_mul_f32_e32 v232, v36, v220
	v_mul_f32_e32 v233, v40, v220
	v_mul_f32_e32 v234, v44, v220
	v_fmac_f32_e32 v232, v37, v221
	v_fmac_f32_e32 v233, v41, v221
	v_fmac_f32_e32 v234, v45, v221
	v_fmac_f32_e32 v232, v38, v222
	v_fmac_f32_e32 v233, v42, v222
	v_fmac_f32_e32 v234, v46, v222
	v_fmac_f32_e32 v232, v39, v223
	v_fmac_f32_e32 v233, v43, v223
	v_fmac_f32_e32 v234, v47, v223
	global_load_dwordx4 v[36:39], v239, s[8:9]
	v_subrev_u32_e32 v239, s14, v239
	global_load_dwordx4 v[40:43], v239, s[8:9]
	v_subrev_u32_e32 v239, s14, v239
	global_load_dwordx4 v[44:47], v239, s[8:9]
	v_subrev_u32_e32 v239, s14, v239
	v_add_f32_dpp v232, v232, v232 quad_perm:[1,0,3,2] row_mask:0xf bank_mask:0xf
	v_add_f32_dpp v233, v233, v233 quad_perm:[1,0,3,2] row_mask:0xf bank_mask:0xf
	v_add_f32_dpp v234, v234, v234 quad_perm:[1,0,3,2] row_mask:0xf bank_mask:0xf
	v_add_f32_dpp v232, v232, v232 quad_perm:[2,3,0,1] row_mask:0xf bank_mask:0xf
	v_add_f32_dpp v233, v233, v233 quad_perm:[2,3,0,1] row_mask:0xf bank_mask:0xf
	v_add_f32_dpp v234, v234, v234 quad_perm:[2,3,0,1] row_mask:0xf bank_mask:0xf
	v_add_f32_dpp v232, v232, v232 row_half_mirror row_mask:0xf bank_mask:0xf
	v_add_f32_dpp v233, v233, v233 row_half_mirror row_mask:0xf bank_mask:0xf
	v_add_f32_dpp v234, v234, v234 row_half_mirror row_mask:0xf bank_mask:0xf
	v_add_f32_dpp v232, v232, v232 row_mirror row_mask:0xf bank_mask:0xf
	v_add_f32_dpp v233, v233, v233 row_mirror row_mask:0xf bank_mask:0xf
	v_add_f32_dpp v234, v234, v234 row_mirror row_mask:0xf bank_mask:0xf
	s_nop 0
	ds_write_b32 v240, v232 offset:480
	ds_write_b32 v240, v233 offset:496
	v_mov_b32_e32 v210, 0xf149f2ca
	v_cndmask_b32_e64 v234, v210, v234, s[24:25]
	ds_write_b32 v240, v234 offset:512
	s_waitcnt lgkmcnt(0)
	ds_read_b32 v245, v72
	ds_read_b32 v246, v72 offset:256
	ds_read_b32 v247, v72 offset:512
	s_waitcnt lgkmcnt(0)
	v_mov_b32_e32 v210, 0xf149f2ca
	v_cmp_gt_u32_e32 vcc, 4, v166
	v_cndmask_b32_e32 v247, v210, v247, vcc
	v_max3_f32 v76, v245, v246, v247
	s_nop 1
	v_max_f32_dpp v76, v76, v76 quad_perm:[1,0,3,2] row_mask:0xf bank_mask:0xf
	s_nop 1
	v_max_f32_dpp v76, v76, v76 quad_perm:[2,3,0,1] row_mask:0xf bank_mask:0xf
	s_nop 1
	v_max_f32_dpp v76, v76, v76 row_half_mirror row_mask:0xf bank_mask:0xf
	s_nop 1
	v_max_f32_dpp v76, v76, v76 row_mirror row_mask:0xf bank_mask:0xf
	s_nop 1
	v_readlane_b32 s0, v76, 0
	v_readlane_b32 s1, v76, 16
	v_readlane_b32 s2, v76, 32
	v_readlane_b32 s3, v76, 48
	s_nop 1
	v_mov_b32_e32 v76, s0
	v_max_f32_e32 v76, s1, v76
	v_max_f32_e32 v76, s2, v76
	v_max_f32_e32 v76, s3, v76
	v_mov_b32_e32 v211, 0xf149f2ca
	v_sub_f32_e32 v210, v245, v76
	v_mul_f32_e32 v210, 0x3fb8aa3b, v210
	v_exp_f32_e32 v210, v210
	s_mov_b32 s0, 0xefa18f08
	v_cmp_lt_f32_e32 vcc, s0, v245
	s_nop 1
	v_cndmask_b32_e32 v245, 0, v210, vcc
	v_sub_f32_e32 v210, v246, v76
	v_mul_f32_e32 v210, 0x3fb8aa3b, v210
	v_exp_f32_e32 v210, v210
	s_mov_b32 s0, 0xefa18f08
	v_cmp_lt_f32_e32 vcc, s0, v246
	s_nop 1
	v_cndmask_b32_e32 v246, 0, v210, vcc
	v_sub_f32_e32 v210, v247, v76
	v_mul_f32_e32 v210, 0x3fb8aa3b, v210
	v_exp_f32_e32 v210, v210
	s_mov_b32 s0, 0xefa18f08
	v_cmp_lt_f32_e32 vcc, s0, v247
	s_nop 1
	v_cndmask_b32_e32 v247, 0, v210, vcc
	v_add_f32_e32 v77, v245, v246
	v_add_f32_e32 v77, v247, v77
	ds_write_b32 v72, v245
	ds_write_b32 v72, v246 offset:256
	s_mov_b64 exec, 0xf
	ds_write_b32 v72, v247 offset:512
	s_mov_b64 exec, s[26:27]
	s_nop 1
	v_add_f32_dpp v77, v77, v77 quad_perm:[1,0,3,2] row_mask:0xf bank_mask:0xf
	s_nop 1
	v_add_f32_dpp v77, v77, v77 quad_perm:[2,3,0,1] row_mask:0xf bank_mask:0xf
	s_nop 1
	v_add_f32_dpp v77, v77, v77 row_half_mirror row_mask:0xf bank_mask:0xf
	s_nop 1
	v_add_f32_dpp v77, v77, v77 row_mirror row_mask:0xf bank_mask:0xf
	s_nop 1
	v_readlane_b32 s0, v77, 0
	v_readlane_b32 s1, v77, 16
	v_readlane_b32 s2, v77, 32
	v_readlane_b32 s3, v77, 48
	s_nop 1
	v_mov_b32_e32 v77, s0
	v_add_f32_e32 v77, s1, v77
	v_add_f32_e32 v77, s2, v77
	v_add_f32_e32 v77, s3, v77
	s_waitcnt lgkmcnt(0)
	v_mov_b32_e32 v228, 0
	v_mov_b32_e32 v229, 0
	v_mov_b32_e32 v230, 0
	v_mov_b32_e32 v231, 0
	ds_read_b32 v235, v240
	ds_read_b32 v236, v240 offset:16
	ds_read_b32 v237, v240 offset:32
	s_waitcnt vmcnt(18)
	s_waitcnt lgkmcnt(0)
	v_fmac_f32_e32 v228, v48, v235
	v_fmac_f32_e32 v229, v49, v235
	v_fmac_f32_e32 v230, v50, v235
	v_fmac_f32_e32 v231, v51, v235
	v_fmac_f32_e32 v228, v52, v236
	v_fmac_f32_e32 v229, v53, v236
	v_fmac_f32_e32 v230, v54, v236
	v_fmac_f32_e32 v231, v55, v236
	v_fmac_f32_e32 v228, v56, v237
	v_fmac_f32_e32 v229, v57, v237
	v_fmac_f32_e32 v230, v58, v237
	v_fmac_f32_e32 v231, v59, v237
	s_and_b32 s19, s86, 1
	s_lshl_b32 s19, s19, 1
	s_add_u32 s19, s19, 1
	s_lshl_b32 s0, s17, 2
	s_add_u32 s0, s0, s19
	s_mul_i32 s0, s0, 0xc00
	s_lshl_b32 s1, s16, 10
	s_add_u32 s0, s0, s1
	s_add_u32 s0, s0, s35
	s_add_u32 s12, s58, 0x86d6000
	s_addc_u32 s13, s59, 0
	s_add_u32 s12, s12, s0
	s_addc_u32 s13, s13, 0
	global_load_dwordx4 v[224:227], v242, s[12:13]
	global_load_dwordx4 v[48:51], v239, s[8:9]
	v_subrev_u32_e32 v239, s14, v239
	global_load_dwordx4 v[52:55], v239, s[8:9]
	v_subrev_u32_e32 v239, s14, v239
	global_load_dwordx4 v[56:59], v239, s[8:9]
	v_subrev_u32_e32 v239, s14, v239
	ds_read_b32 v235, v240 offset:48
	ds_read_b32 v236, v240 offset:64
	ds_read_b32 v237, v240 offset:80
	s_waitcnt vmcnt(19)
	s_waitcnt lgkmcnt(0)
	v_fmac_f32_e32 v228, v60, v235
	v_fmac_f32_e32 v229, v61, v235
	v_fmac_f32_e32 v230, v62, v235
	v_fmac_f32_e32 v231, v63, v235
	v_fmac_f32_e32 v228, v64, v236
	v_fmac_f32_e32 v229, v65, v236
	v_fmac_f32_e32 v230, v66, v236
	v_fmac_f32_e32 v231, v67, v236
	v_fmac_f32_e32 v228, v68, v237
	v_fmac_f32_e32 v229, v69, v237
	v_fmac_f32_e32 v230, v70, v237
	v_fmac_f32_e32 v231, v71, v237
	global_load_dwordx4 v[60:63], v239, s[8:9]
	v_subrev_u32_e32 v239, s14, v239
	global_load_dwordx4 v[64:67], v239, s[8:9]
	v_subrev_u32_e32 v239, s14, v239
	global_load_dwordx4 v[68:71], v239, s[8:9]
	v_subrev_u32_e32 v239, s14, v239
	ds_read_b32 v235, v240 offset:96
	ds_read_b32 v236, v240 offset:112
	ds_read_b32 v237, v240 offset:128
	s_waitcnt vmcnt(19)
	s_waitcnt lgkmcnt(0)
	v_fmac_f32_e32 v228, v196, v235
	v_fmac_f32_e32 v229, v197, v235
	v_fmac_f32_e32 v230, v198, v235
	v_fmac_f32_e32 v231, v199, v235
	v_fmac_f32_e32 v228, v200, v236
	v_fmac_f32_e32 v229, v201, v236
	v_fmac_f32_e32 v230, v202, v236
	v_fmac_f32_e32 v231, v203, v236
	v_fmac_f32_e32 v228, v204, v237
	v_fmac_f32_e32 v229, v205, v237
	v_fmac_f32_e32 v230, v206, v237
	v_fmac_f32_e32 v231, v207, v237
	global_load_dwordx4 v[196:199], v239, s[8:9]
	v_subrev_u32_e32 v239, s14, v239
	global_load_dwordx4 v[200:203], v239, s[8:9]
	v_subrev_u32_e32 v239, s14, v239
	global_load_dwordx4 v[204:207], v239, s[8:9]
	v_subrev_u32_e32 v239, s14, v239
	ds_read_b32 v235, v240 offset:144
	ds_read_b32 v236, v240 offset:160
	ds_read_b32 v237, v240 offset:176
	s_waitcnt vmcnt(19)
	s_waitcnt lgkmcnt(0)
	v_fmac_f32_e32 v228, v0, v235
	v_fmac_f32_e32 v229, v1, v235
	v_fmac_f32_e32 v230, v2, v235
	v_fmac_f32_e32 v231, v3, v235
	v_fmac_f32_e32 v228, v4, v236
	v_fmac_f32_e32 v229, v5, v236
	v_fmac_f32_e32 v230, v6, v236
	v_fmac_f32_e32 v231, v7, v236
	v_fmac_f32_e32 v228, v8, v237
	v_fmac_f32_e32 v229, v9, v237
	v_fmac_f32_e32 v230, v10, v237
	v_fmac_f32_e32 v231, v11, v237
	global_load_dwordx4 v[0:3], v239, s[8:9]
	v_subrev_u32_e32 v239, s14, v239
	global_load_dwordx4 v[4:7], v239, s[8:9]
	s_and_b32 s19, s86, 1
	s_lshl_b32 s19, s19, 1
	s_lshl_b32 s0, s19, 11
	v_mov_b32_e32 v210, s0
	v_cmp_eq_u32_e32 vcc, 0, v241
	v_cndmask_b32_e32 v239, 0, v210, vcc
	v_add_u32_e32 v239, v239, v242
	global_load_dwordx4 v[8:11], v239, s[8:9]
	ds_read_b32 v235, v240 offset:192
	ds_read_b32 v236, v240 offset:208
	ds_read_b32 v237, v240 offset:224
	s_waitcnt vmcnt(19)
	s_waitcnt lgkmcnt(0)
	v_fmac_f32_e32 v228, v12, v235
	v_fmac_f32_e32 v229, v13, v235
	v_fmac_f32_e32 v230, v14, v235
	v_fmac_f32_e32 v231, v15, v235
	v_fmac_f32_e32 v228, v16, v236
	v_fmac_f32_e32 v229, v17, v236
	v_fmac_f32_e32 v230, v18, v236
	v_fmac_f32_e32 v231, v19, v236
	v_fmac_f32_e32 v228, v20, v237
	v_fmac_f32_e32 v229, v21, v237
	v_fmac_f32_e32 v230, v22, v237
	v_fmac_f32_e32 v231, v23, v237
	s_and_b32 s19, s86, 1
	s_lshl_b32 s19, s19, 1
	s_add_u32 s19, s19, 1
	v_lshlrev_b32_e32 v210, s18, v241
	s_add_u32 s0, s15, s19
	v_sub_u32_e32 v210, s0, v210
	v_cmp_le_u32_e32 vcc, s15, v210
	v_lshlrev_b32_e32 v210, 11, v210
	v_add_u32_e32 v210, v210, v242
	v_mov_b32_e32 v212, s6
	v_mov_b32_e32 v213, s7
	v_mov_b32_e32 v214, s10
	v_mov_b32_e32 v215, s11
	v_cndmask_b32_e32 v212, v212, v214, vcc
	v_cndmask_b32_e32 v213, v213, v215, vcc
	v_mov_b32_e32 v211, 0
	v_lshl_add_u64 v[212:213], v[212:213], 0, v[210:211]
	global_load_dwordx4 v[12:15], v[212:213], off
	v_add_u32_e32 v238, 4, v241
	v_lshlrev_b32_e32 v238, s18, v238
	s_add_u32 s0, s15, s19
	v_sub_u32_e32 v238, s0, v238
	v_lshl_add_u32 v238, v238, 11, v242
	global_load_dwordx4 v[16:19], v238, s[6:7]
	v_subrev_u32_e32 v238, s14, v238
	global_load_dwordx4 v[20:23], v238, s[6:7]
	v_subrev_u32_e32 v238, s14, v238
	ds_read_b32 v235, v240 offset:240
	ds_read_b32 v236, v240 offset:256
	ds_read_b32 v237, v240 offset:272
	s_waitcnt vmcnt(19)
	s_waitcnt lgkmcnt(0)
	v_fmac_f32_e32 v228, v24, v235
	v_fmac_f32_e32 v229, v25, v235
	v_fmac_f32_e32 v230, v26, v235
	v_fmac_f32_e32 v231, v27, v235
	v_fmac_f32_e32 v228, v28, v236
	v_fmac_f32_e32 v229, v29, v236
	v_fmac_f32_e32 v230, v30, v236
	v_fmac_f32_e32 v231, v31, v236
	v_fmac_f32_e32 v228, v32, v237
	v_fmac_f32_e32 v229, v33, v237
	v_fmac_f32_e32 v230, v34, v237
	v_fmac_f32_e32 v231, v35, v237
	global_load_dwordx4 v[24:27], v238, s[6:7]
	v_subrev_u32_e32 v238, s14, v238
	global_load_dwordx4 v[28:31], v238, s[6:7]
	v_subrev_u32_e32 v238, s14, v238
	global_load_dwordx4 v[32:35], v238, s[6:7]
	v_subrev_u32_e32 v238, s14, v238
	ds_read_b32 v235, v240 offset:288
	ds_read_b32 v236, v240 offset:304
	ds_read_b32 v237, v240 offset:320
	s_waitcnt vmcnt(19)
	s_waitcnt lgkmcnt(0)
	v_fmac_f32_e32 v228, v36, v235
	v_fmac_f32_e32 v229, v37, v235
	v_fmac_f32_e32 v230, v38, v235
	v_fmac_f32_e32 v231, v39, v235
	v_fmac_f32_e32 v228, v40, v236
	v_fmac_f32_e32 v229, v41, v236
	v_fmac_f32_e32 v230, v42, v236
	v_fmac_f32_e32 v231, v43, v236
	v_fmac_f32_e32 v228, v44, v237
	v_fmac_f32_e32 v229, v45, v237
	v_fmac_f32_e32 v230, v46, v237
	v_fmac_f32_e32 v231, v47, v237
	global_load_dwordx4 v[36:39], v238, s[6:7]
	v_subrev_u32_e32 v238, s14, v238
	global_load_dwordx4 v[40:43], v238, s[6:7]
	v_subrev_u32_e32 v238, s14, v238
	global_load_dwordx4 v[44:47], v238, s[6:7]
	v_subrev_u32_e32 v238, s14, v238
	ds_read_b32 v235, v240 offset:336
	ds_read_b32 v236, v240 offset:352
	ds_read_b32 v237, v240 offset:368
	s_waitcnt vmcnt(18)
	s_waitcnt lgkmcnt(0)
	v_fmac_f32_e32 v228, v48, v235
	v_fmac_f32_e32 v229, v49, v235
	v_fmac_f32_e32 v230, v50, v235
	v_fmac_f32_e32 v231, v51, v235
	v_fmac_f32_e32 v228, v52, v236
	v_fmac_f32_e32 v229, v53, v236
	v_fmac_f32_e32 v230, v54, v236
	v_fmac_f32_e32 v231, v55, v236
	v_fmac_f32_e32 v228, v56, v237
	v_fmac_f32_e32 v229, v57, v237
	v_fmac_f32_e32 v230, v58, v237
	v_fmac_f32_e32 v231, v59, v237
	global_load_dwordx4 v[48:51], v238, s[6:7]
	v_subrev_u32_e32 v238, s14, v238
	global_load_dwordx4 v[52:55], v238, s[6:7]
	v_subrev_u32_e32 v238, s14, v238
	global_load_dwordx4 v[56:59], v238, s[6:7]
	v_subrev_u32_e32 v238, s14, v238
	ds_read_b32 v235, v240 offset:384
	ds_read_b32 v236, v240 offset:400
	ds_read_b32 v237, v240 offset:416
	s_waitcnt vmcnt(18)
	s_waitcnt lgkmcnt(0)
	v_fmac_f32_e32 v228, v60, v235
	v_fmac_f32_e32 v229, v61, v235
	v_fmac_f32_e32 v230, v62, v235
	v_fmac_f32_e32 v231, v63, v235
	v_fmac_f32_e32 v228, v64, v236
	v_fmac_f32_e32 v229, v65, v236
	v_fmac_f32_e32 v230, v66, v236
	v_fmac_f32_e32 v231, v67, v236
	v_fmac_f32_e32 v228, v68, v237
	v_fmac_f32_e32 v229, v69, v237
	v_fmac_f32_e32 v230, v70, v237
	v_fmac_f32_e32 v231, v71, v237
	global_load_dwordx4 v[60:63], v238, s[6:7]
	v_subrev_u32_e32 v238, s14, v238
	global_load_dwordx4 v[64:67], v238, s[6:7]
	v_subrev_u32_e32 v238, s14, v238
	global_load_dwordx4 v[68:71], v238, s[6:7]
	v_subrev_u32_e32 v238, s14, v238
	ds_read_b32 v235, v240 offset:432
	ds_read_b32 v236, v240 offset:448
	ds_read_b32 v237, v240 offset:464
	s_waitcnt vmcnt(18)
	s_waitcnt lgkmcnt(0)
	v_fmac_f32_e32 v228, v196, v235
	v_fmac_f32_e32 v229, v197, v235
	v_fmac_f32_e32 v230, v198, v235
	v_fmac_f32_e32 v231, v199, v235
	v_fmac_f32_e32 v228, v200, v236
	v_fmac_f32_e32 v229, v201, v236
	v_fmac_f32_e32 v230, v202, v236
	v_fmac_f32_e32 v231, v203, v236
	v_fmac_f32_e32 v228, v204, v237
	v_fmac_f32_e32 v229, v205, v237
	v_fmac_f32_e32 v230, v206, v237
	v_fmac_f32_e32 v231, v207, v237
	global_load_dwordx4 v[196:199], v238, s[6:7]
	v_subrev_u32_e32 v238, s14, v238
	global_load_dwordx4 v[200:203], v238, s[6:7]
	v_subrev_u32_e32 v238, s14, v238
	global_load_dwordx4 v[204:207], v238, s[6:7]
	v_subrev_u32_e32 v238, s14, v238
	ds_read_b32 v235, v240 offset:480
	ds_read_b32 v236, v240 offset:496
	ds_read_b32 v237, v240 offset:512
	s_waitcnt vmcnt(18)
	s_waitcnt lgkmcnt(0)
	v_fmac_f32_e32 v228, v0, v235
	v_fmac_f32_e32 v229, v1, v235
	v_fmac_f32_e32 v230, v2, v235
	v_fmac_f32_e32 v231, v3, v235
	v_fmac_f32_e32 v228, v4, v236
	v_fmac_f32_e32 v229, v5, v236
	v_fmac_f32_e32 v230, v6, v236
	v_fmac_f32_e32 v231, v7, v236
	v_fmac_f32_e32 v228, v8, v237
	v_fmac_f32_e32 v229, v9, v237
	v_fmac_f32_e32 v230, v10, v237
	v_fmac_f32_e32 v231, v11, v237
	global_load_dwordx4 v[0:3], v238, s[6:7]
	v_subrev_u32_e32 v238, s14, v238
	global_load_dwordx4 v[4:7], v238, s[6:7]
	v_subrev_u32_e32 v238, s14, v238
	global_load_dwordx4 v[8:11], v238, s[6:7]
	v_subrev_u32_e32 v238, s14, v238
	ds_bpermute_b32 v210, v243, v228
	ds_bpermute_b32 v211, v243, v229
	ds_bpermute_b32 v212, v243, v230
	ds_bpermute_b32 v213, v243, v231
	s_waitcnt lgkmcnt(0)
	v_add_f32_e32 v228, v228, v210
	v_add_f32_e32 v229, v229, v211
	v_add_f32_e32 v230, v230, v212
	v_add_f32_e32 v231, v231, v213
	ds_bpermute_b32 v210, v244, v228
	ds_bpermute_b32 v211, v244, v229
	ds_bpermute_b32 v212, v244, v230
	ds_bpermute_b32 v213, v244, v231
	s_waitcnt lgkmcnt(0)
	v_add_f32_e32 v228, v228, v210
	v_add_f32_e32 v229, v229, v211
	v_add_f32_e32 v230, v230, v212
	v_add_f32_e32 v231, v231, v213
	v_div_scale_f32 v210, s[0:1], v77, v77, 1.0
	v_rcp_f32_e32 v211, v210
	v_div_scale_f32 v212, vcc, 1.0, v77, 1.0
	v_fma_f32 v213, -v210, v211, 1.0
	v_fmac_f32_e32 v211, v213, v211
	v_mul_f32_e32 v213, v212, v211
	v_fma_f32 v214, -v210, v213, v212
	v_fmac_f32_e32 v213, v214, v211
	v_fma_f32 v212, -v210, v213, v212
	v_div_fmas_f32 v212, v212, v211, v213
	v_div_fixup_f32 v212, v212, v77, 1.0
	v_mul_f32_e32 v228, v228, v212
	v_mul_f32_e32 v229, v229, v212
	v_mul_f32_e32 v230, v230, v212
	v_mul_f32_e32 v231, v231, v212
	v_cvt_pk_bf16_f32 v210, v228, v229
	v_cvt_pk_bf16_f32 v211, v230, v231
	s_and_b32 s19, s86, 1
	s_lshl_b32 s19, s19, 1
	s_lshl_b32 s0, s17, 2
	s_add_u32 s0, s0, s19
	s_add_u32 s0, s0, 0x4000
	s_mul_i32 s1, s0, 0xc00
	s_lshl_b32 s2, s16, 9
	s_add_u32 s1, s1, s2
	s_lshl_b32 s2, s34, 7
	s_add_u32 s1, s1, s2
	s_add_u32 s20, s58, 0xdad6000
	s_addc_u32 s21, s59, 0
	s_add_u32 s20, s20, s1
	s_addc_u32 s21, s21, 0
	v_lshrrev_b32_e32 v212, 1, v242
	s_mov_b64 exec, s[24:25]
	global_store_dwordx2 v212, v[210:211], s[20:21]
	s_mul_i32 s1, s0, 48
	s_lshl_b32 s2, s16, 4
	s_add_u32 s1, s1, s2
	s_lshl_b32 s2, s34, 2
	s_add_u32 s1, s1, s2
	s_add_u32 s22, s58, 0x10c56000
	s_addc_u32 s23, s59, 0
	s_add_u32 s22, s22, s1
	s_addc_u32 s23, s23, 0
	v_log_f32_e32 v213, v77
	s_nop 0
	v_mul_f32_e32 v213, 0x3f317218, v213
	v_add_f32_e32 v213, v76, v213
	v_mov_b32_e32 v214, 0
	s_mov_b64 exec, 1
	global_store_dword v214, v213, s[22:23]
	s_mov_b64 exec, s[26:27]
	s_waitcnt vmcnt(20)
	s_waitcnt vmcnt(35)
	v_mul_f32_e32 v224, 0x3e000000, v224
	v_mul_f32_e32 v225, 0x3e000000, v225
	v_mul_f32_e32 v226, 0x3e000000, v226
	v_mul_f32_e32 v227, 0x3e000000, v227
	v_mul_f32_e32 v232, v12, v224
	v_mul_f32_e32 v233, v16, v224
	v_mul_f32_e32 v234, v20, v224
	v_fmac_f32_e32 v232, v13, v225
	v_fmac_f32_e32 v233, v17, v225
	v_fmac_f32_e32 v234, v21, v225
	v_fmac_f32_e32 v232, v14, v226
	v_fmac_f32_e32 v233, v18, v226
	v_fmac_f32_e32 v234, v22, v226
	v_fmac_f32_e32 v232, v15, v227
	v_fmac_f32_e32 v233, v19, v227
	v_fmac_f32_e32 v234, v23, v227
	global_load_dwordx4 v[12:15], v238, s[6:7]
	v_subrev_u32_e32 v238, s14, v238
	global_load_dwordx4 v[16:19], v238, s[6:7]
	v_subrev_u32_e32 v238, s14, v238
	global_load_dwordx4 v[20:23], v238, s[6:7]
	v_subrev_u32_e32 v238, s14, v238
	v_add_f32_dpp v232, v232, v232 quad_perm:[1,0,3,2] row_mask:0xf bank_mask:0xf
	v_add_f32_dpp v233, v233, v233 quad_perm:[1,0,3,2] row_mask:0xf bank_mask:0xf
	v_add_f32_dpp v234, v234, v234 quad_perm:[1,0,3,2] row_mask:0xf bank_mask:0xf
	v_add_f32_dpp v232, v232, v232 quad_perm:[2,3,0,1] row_mask:0xf bank_mask:0xf
	v_add_f32_dpp v233, v233, v233 quad_perm:[2,3,0,1] row_mask:0xf bank_mask:0xf
	v_add_f32_dpp v234, v234, v234 quad_perm:[2,3,0,1] row_mask:0xf bank_mask:0xf
	v_add_f32_dpp v232, v232, v232 row_half_mirror row_mask:0xf bank_mask:0xf
	v_add_f32_dpp v233, v233, v233 row_half_mirror row_mask:0xf bank_mask:0xf
	v_add_f32_dpp v234, v234, v234 row_half_mirror row_mask:0xf bank_mask:0xf
	v_add_f32_dpp v232, v232, v232 row_mirror row_mask:0xf bank_mask:0xf
	v_add_f32_dpp v233, v233, v233 row_mirror row_mask:0xf bank_mask:0xf
	v_add_f32_dpp v234, v234, v234 row_mirror row_mask:0xf bank_mask:0xf
	s_nop 0
	ds_write_b32 v240, v232
	ds_write_b32 v240, v233 offset:16
	ds_write_b32 v240, v234 offset:32
	s_waitcnt vmcnt(20)
	v_mul_f32_e32 v232, v24, v224
	v_mul_f32_e32 v233, v28, v224
	v_mul_f32_e32 v234, v32, v224
	v_fmac_f32_e32 v232, v25, v225
	v_fmac_f32_e32 v233, v29, v225
	v_fmac_f32_e32 v234, v33, v225
	v_fmac_f32_e32 v232, v26, v226
	v_fmac_f32_e32 v233, v30, v226
	v_fmac_f32_e32 v234, v34, v226
	v_fmac_f32_e32 v232, v27, v227
	v_fmac_f32_e32 v233, v31, v227
	v_fmac_f32_e32 v234, v35, v227
	global_load_dwordx4 v[24:27], v238, s[6:7]
	v_subrev_u32_e32 v238, s14, v238
	global_load_dwordx4 v[28:31], v238, s[6:7]
	v_subrev_u32_e32 v238, s14, v238
	global_load_dwordx4 v[32:35], v238, s[6:7]
	v_subrev_u32_e32 v238, s14, v238
	v_add_f32_dpp v232, v232, v232 quad_perm:[1,0,3,2] row_mask:0xf bank_mask:0xf
	v_add_f32_dpp v233, v233, v233 quad_perm:[1,0,3,2] row_mask:0xf bank_mask:0xf
	v_add_f32_dpp v234, v234, v234 quad_perm:[1,0,3,2] row_mask:0xf bank_mask:0xf
	v_add_f32_dpp v232, v232, v232 quad_perm:[2,3,0,1] row_mask:0xf bank_mask:0xf
	v_add_f32_dpp v233, v233, v233 quad_perm:[2,3,0,1] row_mask:0xf bank_mask:0xf
	v_add_f32_dpp v234, v234, v234 quad_perm:[2,3,0,1] row_mask:0xf bank_mask:0xf
	v_add_f32_dpp v232, v232, v232 row_half_mirror row_mask:0xf bank_mask:0xf
	v_add_f32_dpp v233, v233, v233 row_half_mirror row_mask:0xf bank_mask:0xf
	v_add_f32_dpp v234, v234, v234 row_half_mirror row_mask:0xf bank_mask:0xf
	v_add_f32_dpp v232, v232, v232 row_mirror row_mask:0xf bank_mask:0xf
	v_add_f32_dpp v233, v233, v233 row_mirror row_mask:0xf bank_mask:0xf
	v_add_f32_dpp v234, v234, v234 row_mirror row_mask:0xf bank_mask:0xf
	s_nop 0
	ds_write_b32 v240, v232 offset:48
	ds_write_b32 v240, v233 offset:64
	ds_write_b32 v240, v234 offset:80
	s_waitcnt vmcnt(20)
	v_mul_f32_e32 v232, v36, v224
	v_mul_f32_e32 v233, v40, v224
	v_mul_f32_e32 v234, v44, v224
	v_fmac_f32_e32 v232, v37, v225
	v_fmac_f32_e32 v233, v41, v225
	v_fmac_f32_e32 v234, v45, v225
	v_fmac_f32_e32 v232, v38, v226
	v_fmac_f32_e32 v233, v42, v226
	v_fmac_f32_e32 v234, v46, v226
	v_fmac_f32_e32 v232, v39, v227
	v_fmac_f32_e32 v233, v43, v227
	v_fmac_f32_e32 v234, v47, v227
	global_load_dwordx4 v[36:39], v238, s[6:7]
	v_subrev_u32_e32 v238, s14, v238
	global_load_dwordx4 v[40:43], v238, s[6:7]
	v_subrev_u32_e32 v238, s14, v238
	global_load_dwordx4 v[44:47], v238, s[6:7]
	v_subrev_u32_e32 v238, s14, v238
	v_add_f32_dpp v232, v232, v232 quad_perm:[1,0,3,2] row_mask:0xf bank_mask:0xf
	v_add_f32_dpp v233, v233, v233 quad_perm:[1,0,3,2] row_mask:0xf bank_mask:0xf
	v_add_f32_dpp v234, v234, v234 quad_perm:[1,0,3,2] row_mask:0xf bank_mask:0xf
	v_add_f32_dpp v232, v232, v232 quad_perm:[2,3,0,1] row_mask:0xf bank_mask:0xf
	v_add_f32_dpp v233, v233, v233 quad_perm:[2,3,0,1] row_mask:0xf bank_mask:0xf
	v_add_f32_dpp v234, v234, v234 quad_perm:[2,3,0,1] row_mask:0xf bank_mask:0xf
	v_add_f32_dpp v232, v232, v232 row_half_mirror row_mask:0xf bank_mask:0xf
	v_add_f32_dpp v233, v233, v233 row_half_mirror row_mask:0xf bank_mask:0xf
	v_add_f32_dpp v234, v234, v234 row_half_mirror row_mask:0xf bank_mask:0xf
	v_add_f32_dpp v232, v232, v232 row_mirror row_mask:0xf bank_mask:0xf
	v_add_f32_dpp v233, v233, v233 row_mirror row_mask:0xf bank_mask:0xf
	v_add_f32_dpp v234, v234, v234 row_mirror row_mask:0xf bank_mask:0xf
	s_nop 0
	ds_write_b32 v240, v232 offset:96
	ds_write_b32 v240, v233 offset:112
	ds_write_b32 v240, v234 offset:128
	s_waitcnt vmcnt(20)
	v_mul_f32_e32 v232, v48, v224
	v_mul_f32_e32 v233, v52, v224
	v_mul_f32_e32 v234, v56, v224
	v_fmac_f32_e32 v232, v49, v225
	v_fmac_f32_e32 v233, v53, v225
	v_fmac_f32_e32 v234, v57, v225
	v_fmac_f32_e32 v232, v50, v226
	v_fmac_f32_e32 v233, v54, v226
	v_fmac_f32_e32 v234, v58, v226
	v_fmac_f32_e32 v232, v51, v227
	v_fmac_f32_e32 v233, v55, v227
	v_fmac_f32_e32 v234, v59, v227
	global_load_dwordx4 v[48:51], v238, s[6:7]
	v_subrev_u32_e32 v238, s14, v238
	global_load_dwordx4 v[52:55], v238, s[6:7]
	s_and_b32 s19, s86, 1
	s_lshl_b32 s19, s19, 1
	s_add_u32 s19, s19, 1
	s_lshl_b32 s0, s19, 11
	v_mov_b32_e32 v210, s0
	v_cmp_eq_u32_e32 vcc, 0, v241
	v_cndmask_b32_e32 v238, 0, v210, vcc
	v_add_u32_e32 v238, v238, v242
	global_load_dwordx4 v[56:59], v238, s[6:7]
	v_add_f32_dpp v232, v232, v232 quad_perm:[1,0,3,2] row_mask:0xf bank_mask:0xf
	v_add_f32_dpp v233, v233, v233 quad_perm:[1,0,3,2] row_mask:0xf bank_mask:0xf
	v_add_f32_dpp v234, v234, v234 quad_perm:[1,0,3,2] row_mask:0xf bank_mask:0xf
	v_add_f32_dpp v232, v232, v232 quad_perm:[2,3,0,1] row_mask:0xf bank_mask:0xf
	v_add_f32_dpp v233, v233, v233 quad_perm:[2,3,0,1] row_mask:0xf bank_mask:0xf
	v_add_f32_dpp v234, v234, v234 quad_perm:[2,3,0,1] row_mask:0xf bank_mask:0xf
	v_add_f32_dpp v232, v232, v232 row_half_mirror row_mask:0xf bank_mask:0xf
	v_add_f32_dpp v233, v233, v233 row_half_mirror row_mask:0xf bank_mask:0xf
	v_add_f32_dpp v234, v234, v234 row_half_mirror row_mask:0xf bank_mask:0xf
	v_add_f32_dpp v232, v232, v232 row_mirror row_mask:0xf bank_mask:0xf
	v_add_f32_dpp v233, v233, v233 row_mirror row_mask:0xf bank_mask:0xf
	v_add_f32_dpp v234, v234, v234 row_mirror row_mask:0xf bank_mask:0xf
	s_nop 0
	ds_write_b32 v240, v232 offset:144
	ds_write_b32 v240, v233 offset:160
	ds_write_b32 v240, v234 offset:176
	s_waitcnt vmcnt(20)
	v_mul_f32_e32 v232, v60, v224
	v_mul_f32_e32 v233, v64, v224
	v_mul_f32_e32 v234, v68, v224
	v_fmac_f32_e32 v232, v61, v225
	v_fmac_f32_e32 v233, v65, v225
	v_fmac_f32_e32 v234, v69, v225
	v_fmac_f32_e32 v232, v62, v226
	v_fmac_f32_e32 v233, v66, v226
	v_fmac_f32_e32 v234, v70, v226
	v_fmac_f32_e32 v232, v63, v227
	v_fmac_f32_e32 v233, v67, v227
	v_fmac_f32_e32 v234, v71, v227
	s_and_b32 s19, s86, 1
	s_lshl_b32 s19, s19, 1
	s_add_u32 s19, s19, 1
	v_lshlrev_b32_e32 v210, s18, v241
	s_add_u32 s0, s15, s19
	v_sub_u32_e32 v210, s0, v210
	v_cmp_le_u32_e32 vcc, s15, v210
	v_lshlrev_b32_e32 v210, 11, v210
	v_add_u32_e32 v210, v210, v242
	v_add_u32_e32 v210, 0x400, v210
	v_mov_b32_e32 v212, s6
	v_mov_b32_e32 v213, s7
	v_mov_b32_e32 v214, s10
	v_mov_b32_e32 v215, s11
	v_cndmask_b32_e32 v212, v212, v214, vcc
	v_cndmask_b32_e32 v213, v213, v215, vcc
	v_mov_b32_e32 v211, 0
	v_lshl_add_u64 v[212:213], v[212:213], 0, v[210:211]
	global_load_dwordx4 v[60:63], v[212:213], off
	v_add_u32_e32 v239, 4, v241
	v_lshlrev_b32_e32 v239, s18, v239
	s_add_u32 s0, s15, s19
	v_sub_u32_e32 v239, s0, v239
	v_lshl_add_u32 v239, v239, 11, v242
	global_load_dwordx4 v[64:67], v239, s[8:9]
	v_subrev_u32_e32 v239, s14, v239
	global_load_dwordx4 v[68:71], v239, s[8:9]
	v_subrev_u32_e32 v239, s14, v239
	v_add_f32_dpp v232, v232, v232 quad_perm:[1,0,3,2] row_mask:0xf bank_mask:0xf
	v_add_f32_dpp v233, v233, v233 quad_perm:[1,0,3,2] row_mask:0xf bank_mask:0xf
	v_add_f32_dpp v234, v234, v234 quad_perm:[1,0,3,2] row_mask:0xf bank_mask:0xf
	v_add_f32_dpp v232, v232, v232 quad_perm:[2,3,0,1] row_mask:0xf bank_mask:0xf
	v_add_f32_dpp v233, v233, v233 quad_perm:[2,3,0,1] row_mask:0xf bank_mask:0xf
	v_add_f32_dpp v234, v234, v234 quad_perm:[2,3,0,1] row_mask:0xf bank_mask:0xf
	v_add_f32_dpp v232, v232, v232 row_half_mirror row_mask:0xf bank_mask:0xf
	v_add_f32_dpp v233, v233, v233 row_half_mirror row_mask:0xf bank_mask:0xf
	v_add_f32_dpp v234, v234, v234 row_half_mirror row_mask:0xf bank_mask:0xf
	v_add_f32_dpp v232, v232, v232 row_mirror row_mask:0xf bank_mask:0xf
	v_add_f32_dpp v233, v233, v233 row_mirror row_mask:0xf bank_mask:0xf
	v_add_f32_dpp v234, v234, v234 row_mirror row_mask:0xf bank_mask:0xf
	s_nop 0
	ds_write_b32 v240, v232 offset:192
	ds_write_b32 v240, v233 offset:208
	ds_write_b32 v240, v234 offset:224
	s_waitcnt vmcnt(20)
	v_mul_f32_e32 v232, v196, v224
	v_mul_f32_e32 v233, v200, v224
	v_mul_f32_e32 v234, v204, v224
	v_fmac_f32_e32 v232, v197, v225
	v_fmac_f32_e32 v233, v201, v225
	v_fmac_f32_e32 v234, v205, v225
	v_fmac_f32_e32 v232, v198, v226
	v_fmac_f32_e32 v233, v202, v226
	v_fmac_f32_e32 v234, v206, v226
	v_fmac_f32_e32 v232, v199, v227
	v_fmac_f32_e32 v233, v203, v227
	v_fmac_f32_e32 v234, v207, v227
	global_load_dwordx4 v[196:199], v239, s[8:9]
	v_subrev_u32_e32 v239, s14, v239
	global_load_dwordx4 v[200:203], v239, s[8:9]
	v_subrev_u32_e32 v239, s14, v239
	global_load_dwordx4 v[204:207], v239, s[8:9]
	v_subrev_u32_e32 v239, s14, v239
	v_add_f32_dpp v232, v232, v232 quad_perm:[1,0,3,2] row_mask:0xf bank_mask:0xf
	v_add_f32_dpp v233, v233, v233 quad_perm:[1,0,3,2] row_mask:0xf bank_mask:0xf
	v_add_f32_dpp v234, v234, v234 quad_perm:[1,0,3,2] row_mask:0xf bank_mask:0xf
	v_add_f32_dpp v232, v232, v232 quad_perm:[2,3,0,1] row_mask:0xf bank_mask:0xf
	v_add_f32_dpp v233, v233, v233 quad_perm:[2,3,0,1] row_mask:0xf bank_mask:0xf
	v_add_f32_dpp v234, v234, v234 quad_perm:[2,3,0,1] row_mask:0xf bank_mask:0xf
	v_add_f32_dpp v232, v232, v232 row_half_mirror row_mask:0xf bank_mask:0xf
	v_add_f32_dpp v233, v233, v233 row_half_mirror row_mask:0xf bank_mask:0xf
	v_add_f32_dpp v234, v234, v234 row_half_mirror row_mask:0xf bank_mask:0xf
	v_add_f32_dpp v232, v232, v232 row_mirror row_mask:0xf bank_mask:0xf
	v_add_f32_dpp v233, v233, v233 row_mirror row_mask:0xf bank_mask:0xf
	v_add_f32_dpp v234, v234, v234 row_mirror row_mask:0xf bank_mask:0xf
	s_nop 0
	ds_write_b32 v240, v232 offset:240
	ds_write_b32 v240, v233 offset:256
	ds_write_b32 v240, v234 offset:272
	s_waitcnt vmcnt(20)
	v_mul_f32_e32 v232, v0, v224
	v_mul_f32_e32 v233, v4, v224
	v_mul_f32_e32 v234, v8, v224
	v_fmac_f32_e32 v232, v1, v225
	v_fmac_f32_e32 v233, v5, v225
	v_fmac_f32_e32 v234, v9, v225
	v_fmac_f32_e32 v232, v2, v226
	v_fmac_f32_e32 v233, v6, v226
	v_fmac_f32_e32 v234, v10, v226
	v_fmac_f32_e32 v232, v3, v227
	v_fmac_f32_e32 v233, v7, v227
	v_fmac_f32_e32 v234, v11, v227
	global_load_dwordx4 v[0:3], v239, s[8:9]
	v_subrev_u32_e32 v239, s14, v239
	global_load_dwordx4 v[4:7], v239, s[8:9]
	v_subrev_u32_e32 v239, s14, v239
	global_load_dwordx4 v[8:11], v239, s[8:9]
	v_subrev_u32_e32 v239, s14, v239
	v_add_f32_dpp v232, v232, v232 quad_perm:[1,0,3,2] row_mask:0xf bank_mask:0xf
	v_add_f32_dpp v233, v233, v233 quad_perm:[1,0,3,2] row_mask:0xf bank_mask:0xf
	v_add_f32_dpp v234, v234, v234 quad_perm:[1,0,3,2] row_mask:0xf bank_mask:0xf
	v_add_f32_dpp v232, v232, v232 quad_perm:[2,3,0,1] row_mask:0xf bank_mask:0xf
	v_add_f32_dpp v233, v233, v233 quad_perm:[2,3,0,1] row_mask:0xf bank_mask:0xf
	v_add_f32_dpp v234, v234, v234 quad_perm:[2,3,0,1] row_mask:0xf bank_mask:0xf
	v_add_f32_dpp v232, v232, v232 row_half_mirror row_mask:0xf bank_mask:0xf
	v_add_f32_dpp v233, v233, v233 row_half_mirror row_mask:0xf bank_mask:0xf
	v_add_f32_dpp v234, v234, v234 row_half_mirror row_mask:0xf bank_mask:0xf
	v_add_f32_dpp v232, v232, v232 row_mirror row_mask:0xf bank_mask:0xf
	v_add_f32_dpp v233, v233, v233 row_mirror row_mask:0xf bank_mask:0xf
	v_add_f32_dpp v234, v234, v234 row_mirror row_mask:0xf bank_mask:0xf
	s_nop 0
	ds_write_b32 v240, v232 offset:288
	ds_write_b32 v240, v233 offset:304
	ds_write_b32 v240, v234 offset:320
	s_waitcnt vmcnt(18)
	v_mul_f32_e32 v232, v12, v224
	v_mul_f32_e32 v233, v16, v224
	v_mul_f32_e32 v234, v20, v224
	v_fmac_f32_e32 v232, v13, v225
	v_fmac_f32_e32 v233, v17, v225
	v_fmac_f32_e32 v234, v21, v225
	v_fmac_f32_e32 v232, v14, v226
	v_fmac_f32_e32 v233, v18, v226
	v_fmac_f32_e32 v234, v22, v226
	v_fmac_f32_e32 v232, v15, v227
	v_fmac_f32_e32 v233, v19, v227
	v_fmac_f32_e32 v234, v23, v227
	global_load_dwordx4 v[12:15], v239, s[8:9]
	v_subrev_u32_e32 v239, s14, v239
	global_load_dwordx4 v[16:19], v239, s[8:9]
	v_subrev_u32_e32 v239, s14, v239
	global_load_dwordx4 v[20:23], v239, s[8:9]
	v_subrev_u32_e32 v239, s14, v239
	v_add_f32_dpp v232, v232, v232 quad_perm:[1,0,3,2] row_mask:0xf bank_mask:0xf
	v_add_f32_dpp v233, v233, v233 quad_perm:[1,0,3,2] row_mask:0xf bank_mask:0xf
	v_add_f32_dpp v234, v234, v234 quad_perm:[1,0,3,2] row_mask:0xf bank_mask:0xf
	v_add_f32_dpp v232, v232, v232 quad_perm:[2,3,0,1] row_mask:0xf bank_mask:0xf
	v_add_f32_dpp v233, v233, v233 quad_perm:[2,3,0,1] row_mask:0xf bank_mask:0xf
	v_add_f32_dpp v234, v234, v234 quad_perm:[2,3,0,1] row_mask:0xf bank_mask:0xf
	v_add_f32_dpp v232, v232, v232 row_half_mirror row_mask:0xf bank_mask:0xf
	v_add_f32_dpp v233, v233, v233 row_half_mirror row_mask:0xf bank_mask:0xf
	v_add_f32_dpp v234, v234, v234 row_half_mirror row_mask:0xf bank_mask:0xf
	v_add_f32_dpp v232, v232, v232 row_mirror row_mask:0xf bank_mask:0xf
	v_add_f32_dpp v233, v233, v233 row_mirror row_mask:0xf bank_mask:0xf
	v_add_f32_dpp v234, v234, v234 row_mirror row_mask:0xf bank_mask:0xf
	s_nop 0
	ds_write_b32 v240, v232 offset:336
	ds_write_b32 v240, v233 offset:352
	ds_write_b32 v240, v234 offset:368
	s_waitcnt vmcnt(18)
	v_mul_f32_e32 v232, v24, v224
	v_mul_f32_e32 v233, v28, v224
	v_mul_f32_e32 v234, v32, v224
	v_fmac_f32_e32 v232, v25, v225
	v_fmac_f32_e32 v233, v29, v225
	v_fmac_f32_e32 v234, v33, v225
	v_fmac_f32_e32 v232, v26, v226
	v_fmac_f32_e32 v233, v30, v226
	v_fmac_f32_e32 v234, v34, v226
	v_fmac_f32_e32 v232, v27, v227
	v_fmac_f32_e32 v233, v31, v227
	v_fmac_f32_e32 v234, v35, v227
	global_load_dwordx4 v[24:27], v239, s[8:9]
	v_subrev_u32_e32 v239, s14, v239
	global_load_dwordx4 v[28:31], v239, s[8:9]
	v_subrev_u32_e32 v239, s14, v239
	global_load_dwordx4 v[32:35], v239, s[8:9]
	v_subrev_u32_e32 v239, s14, v239
	v_add_f32_dpp v232, v232, v232 quad_perm:[1,0,3,2] row_mask:0xf bank_mask:0xf
	v_add_f32_dpp v233, v233, v233 quad_perm:[1,0,3,2] row_mask:0xf bank_mask:0xf
	v_add_f32_dpp v234, v234, v234 quad_perm:[1,0,3,2] row_mask:0xf bank_mask:0xf
	v_add_f32_dpp v232, v232, v232 quad_perm:[2,3,0,1] row_mask:0xf bank_mask:0xf
	v_add_f32_dpp v233, v233, v233 quad_perm:[2,3,0,1] row_mask:0xf bank_mask:0xf
	v_add_f32_dpp v234, v234, v234 quad_perm:[2,3,0,1] row_mask:0xf bank_mask:0xf
	v_add_f32_dpp v232, v232, v232 row_half_mirror row_mask:0xf bank_mask:0xf
	v_add_f32_dpp v233, v233, v233 row_half_mirror row_mask:0xf bank_mask:0xf
	v_add_f32_dpp v234, v234, v234 row_half_mirror row_mask:0xf bank_mask:0xf
	v_add_f32_dpp v232, v232, v232 row_mirror row_mask:0xf bank_mask:0xf
	v_add_f32_dpp v233, v233, v233 row_mirror row_mask:0xf bank_mask:0xf
	v_add_f32_dpp v234, v234, v234 row_mirror row_mask:0xf bank_mask:0xf
	s_nop 0
	ds_write_b32 v240, v232 offset:384
	ds_write_b32 v240, v233 offset:400
	ds_write_b32 v240, v234 offset:416
	s_waitcnt vmcnt(18)
	v_mul_f32_e32 v232, v36, v224
	v_mul_f32_e32 v233, v40, v224
	v_mul_f32_e32 v234, v44, v224
	v_fmac_f32_e32 v232, v37, v225
	v_fmac_f32_e32 v233, v41, v225
	v_fmac_f32_e32 v234, v45, v225
	v_fmac_f32_e32 v232, v38, v226
	v_fmac_f32_e32 v233, v42, v226
	v_fmac_f32_e32 v234, v46, v226
	v_fmac_f32_e32 v232, v39, v227
	v_fmac_f32_e32 v233, v43, v227
	v_fmac_f32_e32 v234, v47, v227
	global_load_dwordx4 v[36:39], v239, s[8:9]
	v_subrev_u32_e32 v239, s14, v239
	global_load_dwordx4 v[40:43], v239, s[8:9]
	v_subrev_u32_e32 v239, s14, v239
	global_load_dwordx4 v[44:47], v239, s[8:9]
	v_subrev_u32_e32 v239, s14, v239
	v_add_f32_dpp v232, v232, v232 quad_perm:[1,0,3,2] row_mask:0xf bank_mask:0xf
	v_add_f32_dpp v233, v233, v233 quad_perm:[1,0,3,2] row_mask:0xf bank_mask:0xf
	v_add_f32_dpp v234, v234, v234 quad_perm:[1,0,3,2] row_mask:0xf bank_mask:0xf
	v_add_f32_dpp v232, v232, v232 quad_perm:[2,3,0,1] row_mask:0xf bank_mask:0xf
	v_add_f32_dpp v233, v233, v233 quad_perm:[2,3,0,1] row_mask:0xf bank_mask:0xf
	v_add_f32_dpp v234, v234, v234 quad_perm:[2,3,0,1] row_mask:0xf bank_mask:0xf
	v_add_f32_dpp v232, v232, v232 row_half_mirror row_mask:0xf bank_mask:0xf
	v_add_f32_dpp v233, v233, v233 row_half_mirror row_mask:0xf bank_mask:0xf
	v_add_f32_dpp v234, v234, v234 row_half_mirror row_mask:0xf bank_mask:0xf
	v_add_f32_dpp v232, v232, v232 row_mirror row_mask:0xf bank_mask:0xf
	v_add_f32_dpp v233, v233, v233 row_mirror row_mask:0xf bank_mask:0xf
	v_add_f32_dpp v234, v234, v234 row_mirror row_mask:0xf bank_mask:0xf
	s_nop 0
	ds_write_b32 v240, v232 offset:432
	ds_write_b32 v240, v233 offset:448
	ds_write_b32 v240, v234 offset:464
	s_waitcnt vmcnt(18)
	v_mul_f32_e32 v232, v48, v224
	v_mul_f32_e32 v233, v52, v224
	v_mul_f32_e32 v234, v56, v224
	v_fmac_f32_e32 v232, v49, v225
	v_fmac_f32_e32 v233, v53, v225
	v_fmac_f32_e32 v234, v57, v225
	v_fmac_f32_e32 v232, v50, v226
	v_fmac_f32_e32 v233, v54, v226
	v_fmac_f32_e32 v234, v58, v226
	v_fmac_f32_e32 v232, v51, v227
	v_fmac_f32_e32 v233, v55, v227
	v_fmac_f32_e32 v234, v59, v227
	global_load_dwordx4 v[48:51], v239, s[8:9]
	v_subrev_u32_e32 v239, s14, v239
	global_load_dwordx4 v[52:55], v239, s[8:9]
	v_subrev_u32_e32 v239, s14, v239
	global_load_dwordx4 v[56:59], v239, s[8:9]
	v_subrev_u32_e32 v239, s14, v239
	v_add_f32_dpp v232, v232, v232 quad_perm:[1,0,3,2] row_mask:0xf bank_mask:0xf
	v_add_f32_dpp v233, v233, v233 quad_perm:[1,0,3,2] row_mask:0xf bank_mask:0xf
	v_add_f32_dpp v234, v234, v234 quad_perm:[1,0,3,2] row_mask:0xf bank_mask:0xf
	v_add_f32_dpp v232, v232, v232 quad_perm:[2,3,0,1] row_mask:0xf bank_mask:0xf
	v_add_f32_dpp v233, v233, v233 quad_perm:[2,3,0,1] row_mask:0xf bank_mask:0xf
	v_add_f32_dpp v234, v234, v234 quad_perm:[2,3,0,1] row_mask:0xf bank_mask:0xf
	v_add_f32_dpp v232, v232, v232 row_half_mirror row_mask:0xf bank_mask:0xf
	v_add_f32_dpp v233, v233, v233 row_half_mirror row_mask:0xf bank_mask:0xf
	v_add_f32_dpp v234, v234, v234 row_half_mirror row_mask:0xf bank_mask:0xf
	v_add_f32_dpp v232, v232, v232 row_mirror row_mask:0xf bank_mask:0xf
	v_add_f32_dpp v233, v233, v233 row_mirror row_mask:0xf bank_mask:0xf
	v_add_f32_dpp v234, v234, v234 row_mirror row_mask:0xf bank_mask:0xf
	s_nop 0
	ds_write_b32 v240, v232 offset:480
	ds_write_b32 v240, v233 offset:496
	v_mov_b32_e32 v210, 0xf149f2ca
	v_cndmask_b32_e64 v234, v210, v234, s[24:25]
	ds_write_b32 v240, v234 offset:512
	s_waitcnt lgkmcnt(0)
	ds_read_b32 v245, v72
	ds_read_b32 v246, v72 offset:256
	ds_read_b32 v247, v72 offset:512
	s_waitcnt lgkmcnt(0)
	v_mov_b32_e32 v210, 0xf149f2ca
	v_cmp_gt_u32_e32 vcc, 4, v166
	v_cndmask_b32_e32 v247, v210, v247, vcc
	v_max3_f32 v76, v245, v246, v247
	s_nop 1
	v_max_f32_dpp v76, v76, v76 quad_perm:[1,0,3,2] row_mask:0xf bank_mask:0xf
	s_nop 1
	v_max_f32_dpp v76, v76, v76 quad_perm:[2,3,0,1] row_mask:0xf bank_mask:0xf
	s_nop 1
	v_max_f32_dpp v76, v76, v76 row_half_mirror row_mask:0xf bank_mask:0xf
	s_nop 1
	v_max_f32_dpp v76, v76, v76 row_mirror row_mask:0xf bank_mask:0xf
	s_nop 1
	v_readlane_b32 s0, v76, 0
	v_readlane_b32 s1, v76, 16
	v_readlane_b32 s2, v76, 32
	v_readlane_b32 s3, v76, 48
	s_nop 1
	v_mov_b32_e32 v76, s0
	v_max_f32_e32 v76, s1, v76
	v_max_f32_e32 v76, s2, v76
	v_max_f32_e32 v76, s3, v76
	v_mov_b32_e32 v211, 0xf149f2ca
	v_sub_f32_e32 v210, v245, v76
	v_mul_f32_e32 v210, 0x3fb8aa3b, v210
	v_exp_f32_e32 v210, v210
	s_mov_b32 s0, 0xefa18f08
	v_cmp_lt_f32_e32 vcc, s0, v245
	s_nop 1
	v_cndmask_b32_e32 v245, 0, v210, vcc
	v_sub_f32_e32 v210, v246, v76
	v_mul_f32_e32 v210, 0x3fb8aa3b, v210
	v_exp_f32_e32 v210, v210
	s_mov_b32 s0, 0xefa18f08
	v_cmp_lt_f32_e32 vcc, s0, v246
	s_nop 1
	v_cndmask_b32_e32 v246, 0, v210, vcc
	v_sub_f32_e32 v210, v247, v76
	v_mul_f32_e32 v210, 0x3fb8aa3b, v210
	v_exp_f32_e32 v210, v210
	s_mov_b32 s0, 0xefa18f08
	v_cmp_lt_f32_e32 vcc, s0, v247
	s_nop 1
	v_cndmask_b32_e32 v247, 0, v210, vcc
	v_add_f32_e32 v77, v245, v246
	v_add_f32_e32 v77, v247, v77
	ds_write_b32 v72, v245
	ds_write_b32 v72, v246 offset:256
	s_mov_b64 exec, 0xf
	ds_write_b32 v72, v247 offset:512
	s_mov_b64 exec, s[26:27]
	s_nop 1
	v_add_f32_dpp v77, v77, v77 quad_perm:[1,0,3,2] row_mask:0xf bank_mask:0xf
	s_nop 1
	v_add_f32_dpp v77, v77, v77 quad_perm:[2,3,0,1] row_mask:0xf bank_mask:0xf
	s_nop 1
	v_add_f32_dpp v77, v77, v77 row_half_mirror row_mask:0xf bank_mask:0xf
	s_nop 1
	v_add_f32_dpp v77, v77, v77 row_mirror row_mask:0xf bank_mask:0xf
	s_nop 1
	v_readlane_b32 s0, v77, 0
	v_readlane_b32 s1, v77, 16
	v_readlane_b32 s2, v77, 32
	v_readlane_b32 s3, v77, 48
	s_nop 1
	v_mov_b32_e32 v77, s0
	v_add_f32_e32 v77, s1, v77
	v_add_f32_e32 v77, s2, v77
	v_add_f32_e32 v77, s3, v77
	s_waitcnt lgkmcnt(0)
	v_mov_b32_e32 v228, 0
	v_mov_b32_e32 v229, 0
	v_mov_b32_e32 v230, 0
	v_mov_b32_e32 v231, 0
	ds_read_b32 v235, v240
	ds_read_b32 v236, v240 offset:16
	ds_read_b32 v237, v240 offset:32
	s_waitcnt vmcnt(18)
	s_waitcnt lgkmcnt(0)
	v_fmac_f32_e32 v228, v60, v235
	v_fmac_f32_e32 v229, v61, v235
	v_fmac_f32_e32 v230, v62, v235
	v_fmac_f32_e32 v231, v63, v235
	v_fmac_f32_e32 v228, v64, v236
	v_fmac_f32_e32 v229, v65, v236
	v_fmac_f32_e32 v230, v66, v236
	v_fmac_f32_e32 v231, v67, v236
	v_fmac_f32_e32 v228, v68, v237
	v_fmac_f32_e32 v229, v69, v237
	v_fmac_f32_e32 v230, v70, v237
	v_fmac_f32_e32 v231, v71, v237
	global_load_dwordx4 v[60:63], v239, s[8:9]
	v_subrev_u32_e32 v239, s14, v239
	global_load_dwordx4 v[64:67], v239, s[8:9]
	v_subrev_u32_e32 v239, s14, v239
	global_load_dwordx4 v[68:71], v239, s[8:9]
	v_subrev_u32_e32 v239, s14, v239
	ds_read_b32 v235, v240 offset:48
	ds_read_b32 v236, v240 offset:64
	ds_read_b32 v237, v240 offset:80
	s_waitcnt vmcnt(18)
	s_waitcnt lgkmcnt(0)
	v_fmac_f32_e32 v228, v196, v235
	v_fmac_f32_e32 v229, v197, v235
	v_fmac_f32_e32 v230, v198, v235
	v_fmac_f32_e32 v231, v199, v235
	v_fmac_f32_e32 v228, v200, v236
	v_fmac_f32_e32 v229, v201, v236
	v_fmac_f32_e32 v230, v202, v236
	v_fmac_f32_e32 v231, v203, v236
	v_fmac_f32_e32 v228, v204, v237
	v_fmac_f32_e32 v229, v205, v237
	v_fmac_f32_e32 v230, v206, v237
	v_fmac_f32_e32 v231, v207, v237
	global_load_dwordx4 v[196:199], v239, s[8:9]
	v_subrev_u32_e32 v239, s14, v239
	global_load_dwordx4 v[200:203], v239, s[8:9]
	v_subrev_u32_e32 v239, s14, v239
	global_load_dwordx4 v[204:207], v239, s[8:9]
	v_subrev_u32_e32 v239, s14, v239
	ds_read_b32 v235, v240 offset:96
	ds_read_b32 v236, v240 offset:112
	ds_read_b32 v237, v240 offset:128
	s_waitcnt vmcnt(18)
	s_waitcnt lgkmcnt(0)
	v_fmac_f32_e32 v228, v0, v235
	v_fmac_f32_e32 v229, v1, v235
	v_fmac_f32_e32 v230, v2, v235
	v_fmac_f32_e32 v231, v3, v235
	v_fmac_f32_e32 v228, v4, v236
	v_fmac_f32_e32 v229, v5, v236
	v_fmac_f32_e32 v230, v6, v236
	v_fmac_f32_e32 v231, v7, v236
	v_fmac_f32_e32 v228, v8, v237
	v_fmac_f32_e32 v229, v9, v237
	v_fmac_f32_e32 v230, v10, v237
	v_fmac_f32_e32 v231, v11, v237
	global_load_dwordx4 v[0:3], v239, s[8:9]
	v_subrev_u32_e32 v239, s14, v239
	global_load_dwordx4 v[4:7], v239, s[8:9]
	v_subrev_u32_e32 v239, s14, v239
	global_load_dwordx4 v[8:11], v239, s[8:9]
	v_subrev_u32_e32 v239, s14, v239
	ds_read_b32 v235, v240 offset:144
	ds_read_b32 v236, v240 offset:160
	ds_read_b32 v237, v240 offset:176
	s_waitcnt vmcnt(18)
	s_waitcnt lgkmcnt(0)
	v_fmac_f32_e32 v228, v12, v235
	v_fmac_f32_e32 v229, v13, v235
	v_fmac_f32_e32 v230, v14, v235
	v_fmac_f32_e32 v231, v15, v235
	v_fmac_f32_e32 v228, v16, v236
	v_fmac_f32_e32 v229, v17, v236
	v_fmac_f32_e32 v230, v18, v236
	v_fmac_f32_e32 v231, v19, v236
	v_fmac_f32_e32 v228, v20, v237
	v_fmac_f32_e32 v229, v21, v237
	v_fmac_f32_e32 v230, v22, v237
	v_fmac_f32_e32 v231, v23, v237
	global_load_dwordx4 v[12:15], v239, s[8:9]
	v_subrev_u32_e32 v239, s14, v239
	global_load_dwordx4 v[16:19], v239, s[8:9]
	s_and_b32 s19, s86, 1
	s_lshl_b32 s19, s19, 1
	s_add_u32 s19, s19, 1
	s_lshl_b32 s0, s19, 11
	v_mov_b32_e32 v210, s0
	v_cmp_eq_u32_e32 vcc, 0, v241
	v_cndmask_b32_e32 v239, 0, v210, vcc
	v_add_u32_e32 v239, v239, v242
	global_load_dwordx4 v[20:23], v239, s[8:9]
	ds_read_b32 v235, v240 offset:192
	ds_read_b32 v236, v240 offset:208
	ds_read_b32 v237, v240 offset:224
	s_waitcnt vmcnt(18)
	s_waitcnt lgkmcnt(0)
	v_fmac_f32_e32 v228, v24, v235
	v_fmac_f32_e32 v229, v25, v235
	v_fmac_f32_e32 v230, v26, v235
	v_fmac_f32_e32 v231, v27, v235
	v_fmac_f32_e32 v228, v28, v236
	v_fmac_f32_e32 v229, v29, v236
	v_fmac_f32_e32 v230, v30, v236
	v_fmac_f32_e32 v231, v31, v236
	v_fmac_f32_e32 v228, v32, v237
	v_fmac_f32_e32 v229, v33, v237
	v_fmac_f32_e32 v230, v34, v237
	v_fmac_f32_e32 v231, v35, v237
	ds_read_b32 v235, v240 offset:240
	ds_read_b32 v236, v240 offset:256
	ds_read_b32 v237, v240 offset:272
	s_waitcnt vmcnt(15)
	s_waitcnt lgkmcnt(0)
	v_fmac_f32_e32 v228, v36, v235
	v_fmac_f32_e32 v229, v37, v235
	v_fmac_f32_e32 v230, v38, v235
	v_fmac_f32_e32 v231, v39, v235
	v_fmac_f32_e32 v228, v40, v236
	v_fmac_f32_e32 v229, v41, v236
	v_fmac_f32_e32 v230, v42, v236
	v_fmac_f32_e32 v231, v43, v236
	v_fmac_f32_e32 v228, v44, v237
	v_fmac_f32_e32 v229, v45, v237
	v_fmac_f32_e32 v230, v46, v237
	v_fmac_f32_e32 v231, v47, v237
	ds_read_b32 v235, v240 offset:288
	ds_read_b32 v236, v240 offset:304
	ds_read_b32 v237, v240 offset:320
	s_waitcnt vmcnt(12)
	s_waitcnt lgkmcnt(0)
	v_fmac_f32_e32 v228, v48, v235
	v_fmac_f32_e32 v229, v49, v235
	v_fmac_f32_e32 v230, v50, v235
	v_fmac_f32_e32 v231, v51, v235
	v_fmac_f32_e32 v228, v52, v236
	v_fmac_f32_e32 v229, v53, v236
	v_fmac_f32_e32 v230, v54, v236
	v_fmac_f32_e32 v231, v55, v236
	v_fmac_f32_e32 v228, v56, v237
	v_fmac_f32_e32 v229, v57, v237
	v_fmac_f32_e32 v230, v58, v237
	v_fmac_f32_e32 v231, v59, v237
	ds_read_b32 v235, v240 offset:336
	ds_read_b32 v236, v240 offset:352
	ds_read_b32 v237, v240 offset:368
	s_waitcnt vmcnt(9)
	s_waitcnt lgkmcnt(0)
	v_fmac_f32_e32 v228, v60, v235
	v_fmac_f32_e32 v229, v61, v235
	v_fmac_f32_e32 v230, v62, v235
	v_fmac_f32_e32 v231, v63, v235
	v_fmac_f32_e32 v228, v64, v236
	v_fmac_f32_e32 v229, v65, v236
	v_fmac_f32_e32 v230, v66, v236
	v_fmac_f32_e32 v231, v67, v236
	v_fmac_f32_e32 v228, v68, v237
	v_fmac_f32_e32 v229, v69, v237
	v_fmac_f32_e32 v230, v70, v237
	v_fmac_f32_e32 v231, v71, v237
	ds_read_b32 v235, v240 offset:384
	ds_read_b32 v236, v240 offset:400
	ds_read_b32 v237, v240 offset:416
	s_waitcnt vmcnt(6)
	s_waitcnt lgkmcnt(0)
	v_fmac_f32_e32 v228, v196, v235
	v_fmac_f32_e32 v229, v197, v235
	v_fmac_f32_e32 v230, v198, v235
	v_fmac_f32_e32 v231, v199, v235
	v_fmac_f32_e32 v228, v200, v236
	v_fmac_f32_e32 v229, v201, v236
	v_fmac_f32_e32 v230, v202, v236
	v_fmac_f32_e32 v231, v203, v236
	v_fmac_f32_e32 v228, v204, v237
	v_fmac_f32_e32 v229, v205, v237
	v_fmac_f32_e32 v230, v206, v237
	v_fmac_f32_e32 v231, v207, v237
	ds_read_b32 v235, v240 offset:432
	ds_read_b32 v236, v240 offset:448
	ds_read_b32 v237, v240 offset:464
	s_waitcnt vmcnt(3)
	s_waitcnt lgkmcnt(0)
	v_fmac_f32_e32 v228, v0, v235
	v_fmac_f32_e32 v229, v1, v235
	v_fmac_f32_e32 v230, v2, v235
	v_fmac_f32_e32 v231, v3, v235
	v_fmac_f32_e32 v228, v4, v236
	v_fmac_f32_e32 v229, v5, v236
	v_fmac_f32_e32 v230, v6, v236
	v_fmac_f32_e32 v231, v7, v236
	v_fmac_f32_e32 v228, v8, v237
	v_fmac_f32_e32 v229, v9, v237
	v_fmac_f32_e32 v230, v10, v237
	v_fmac_f32_e32 v231, v11, v237
	ds_read_b32 v235, v240 offset:480
	ds_read_b32 v236, v240 offset:496
	ds_read_b32 v237, v240 offset:512
	s_waitcnt vmcnt(0)
	s_waitcnt lgkmcnt(0)
	v_fmac_f32_e32 v228, v12, v235
	v_fmac_f32_e32 v229, v13, v235
	v_fmac_f32_e32 v230, v14, v235
	v_fmac_f32_e32 v231, v15, v235
	v_fmac_f32_e32 v228, v16, v236
	v_fmac_f32_e32 v229, v17, v236
	v_fmac_f32_e32 v230, v18, v236
	v_fmac_f32_e32 v231, v19, v236
	v_fmac_f32_e32 v228, v20, v237
	v_fmac_f32_e32 v229, v21, v237
	v_fmac_f32_e32 v230, v22, v237
	v_fmac_f32_e32 v231, v23, v237
	ds_bpermute_b32 v210, v243, v228
	ds_bpermute_b32 v211, v243, v229
	ds_bpermute_b32 v212, v243, v230
	ds_bpermute_b32 v213, v243, v231
	s_waitcnt lgkmcnt(0)
	v_add_f32_e32 v228, v228, v210
	v_add_f32_e32 v229, v229, v211
	v_add_f32_e32 v230, v230, v212
	v_add_f32_e32 v231, v231, v213
	ds_bpermute_b32 v210, v244, v228
	ds_bpermute_b32 v211, v244, v229
	ds_bpermute_b32 v212, v244, v230
	ds_bpermute_b32 v213, v244, v231
	s_waitcnt lgkmcnt(0)
	v_add_f32_e32 v228, v228, v210
	v_add_f32_e32 v229, v229, v211
	v_add_f32_e32 v230, v230, v212
	v_add_f32_e32 v231, v231, v213
	v_div_scale_f32 v210, s[0:1], v77, v77, 1.0
	v_rcp_f32_e32 v211, v210
	v_div_scale_f32 v212, vcc, 1.0, v77, 1.0
	v_fma_f32 v213, -v210, v211, 1.0
	v_fmac_f32_e32 v211, v213, v211
	v_mul_f32_e32 v213, v212, v211
	v_fma_f32 v214, -v210, v213, v212
	v_fmac_f32_e32 v213, v214, v211
	v_fma_f32 v212, -v210, v213, v212
	v_div_fmas_f32 v212, v212, v211, v213
	v_div_fixup_f32 v212, v212, v77, 1.0
	v_mul_f32_e32 v228, v228, v212
	v_mul_f32_e32 v229, v229, v212
	v_mul_f32_e32 v230, v230, v212
	v_mul_f32_e32 v231, v231, v212
	v_cvt_pk_bf16_f32 v210, v228, v229
	v_cvt_pk_bf16_f32 v211, v230, v231
	s_and_b32 s19, s86, 1
	s_lshl_b32 s19, s19, 1
	s_add_u32 s19, s19, 1
	s_lshl_b32 s0, s17, 2
	s_add_u32 s0, s0, s19
	s_add_u32 s0, s0, 0x4000
	s_mul_i32 s1, s0, 0xc00
	s_lshl_b32 s2, s16, 9
	s_add_u32 s1, s1, s2
	s_lshl_b32 s2, s34, 7
	s_add_u32 s1, s1, s2
	s_add_u32 s20, s58, 0xdad6000
	s_addc_u32 s21, s59, 0
	s_add_u32 s20, s20, s1
	s_addc_u32 s21, s21, 0
	v_lshrrev_b32_e32 v212, 1, v242
	s_mov_b64 exec, s[24:25]
	global_store_dwordx2 v212, v[210:211], s[20:21]
	s_mul_i32 s1, s0, 48
	s_lshl_b32 s2, s16, 4
	s_add_u32 s1, s1, s2
	s_lshl_b32 s2, s34, 2
	s_add_u32 s1, s1, s2
	s_add_u32 s22, s58, 0x10c56000
	s_addc_u32 s23, s59, 0
	s_add_u32 s22, s22, s1
	s_addc_u32 s23, s23, 0
	v_log_f32_e32 v213, v77
	s_nop 0
	v_mul_f32_e32 v213, 0x3f317218, v213
	v_add_f32_e32 v213, v76, v213
	v_mov_b32_e32 v214, 0
	s_mov_b64 exec, 1
	global_store_dword v214, v213, s[22:23]
	s_mov_b64 exec, s[26:27]
	s_branch .LBB0_662
